# boustrophedon pair order with srcA-major rows (4 consecutive pairs keep the srcA fragment pair, row turns keep srcB), all four GEMM loops
# baseline (speedup 1.0000x reference)
; #define PG8_STAGE(bufoff, gbase, voff) do { _Pragma("unroll") for (int _i = 0; _i < 2; ++_i) \
;         __builtin_amdgcn_global_load_lds((const unsigned*)((const char*)(gbase) + (voff)[_i]), (PG8_LAS unsigned*)(lds + (bufoff) + ldsw + _i * 8192), 16, 0, 0); } while (0)
; #define PG8_LDA(dst, b, h) do { _Pragma("unroll") for (int m = 0; m < 4; ++m) _Pragma("unroll") for (int k = 0; k < 2; ++k) dst[m][k] = *(const PG8_LAS bf16x8*)(lds + PG8_SA(b, h) + aoff + m * 2048 + k * 1024); } while (0)
; #define PG8_LDB(dst, b, h) do { _Pragma("unroll") for (int n = 0; n < 2; ++n) _Pragma("unroll") for (int k = 0; k < 2; ++k) dst[n][k] = *(const PG8_LAS bf16x8*)(lds + PG8_SB(b, h) + boff + n * 2048 + k * 1024); } while (0)
; #define PG8_MMA(ai, bj, At, Bt) do { __builtin_amdgcn_s_setprio(1); _Pragma("unroll") for (int m = 0; m < 4; ++m) _Pragma("unroll") for (int n = 0; n < 2; ++n) _Pragma("unroll") for (int k = 0; k < 2; ++k) \
;         acc[ai][bj][m][n] = __builtin_amdgcn_mfma_f32_16x16x32_bf16(Bt[n][k], At[m][k], acc[ai][bj][m][n], 0, 0, 0); __builtin_amdgcn_s_setprio(0); } while (0)
; #define PG8_BAR __builtin_amdgcn_s_barrier()
; template <class Epi, class Sched, bool ALIGN_EPI = false, bool SP2 = false>
; __device__ __forceinline__ void gemm_phase(PG8_LAS unsigned char* lds, const Gemm g, const Sched& S, const Epi& E) {
;     ...
;             const bool last = (t == nt - 2);
;             const char* a1 = cA + (size_t)(t + 1) * kstep;
;             const char* a2 = last ? nA : cA + (size_t)(t + 2) * kstep; const char* b2 = last ? nB : cB + (size_t)(t + 2) * kstep;
;             const char* a3 = a2 + kstep; const char* b3 = b2 + kstep;
;             if (last && has_next) S.a_ready(nxt);
;             if constexpr (Epi::MIDK) { if (t == (nt >> 1)) { E.midk(acc, wr, fr); asm volatile("s_waitcnt lgkmcnt(0)" ::: "memory"); } }
;             if constexpr (SP2) {
;             PG8_LDB(B0, 0, 0); PG8_LDB(B1, 0, 1); PG8_SCHED; PG8_LDA(At, 0, 0); PG8_STAGE(PG8_SA(1, 1), a1 + hstep, voffA);
;             PG8_WAIT_V(8); PG8_WAIT_L(0); PG8_BAR; PG8_MMA(0, 0, At, B0); PG8_MMA(0, 1, At, B1); PG8_BAR; PG8_SCHED;
;             PG8_LDA(At, 0, 1); PG8_STAGE(PG8_SB(0, 0), b2, voffB); PG8_STAGE(PG8_SB(0, 1), b2 + hstep, voffB); PG8_STAGE(PG8_SA(0, 0), a2, voffA);
;             PG8_WAIT_V(8); PG8_WAIT_L(0); PG8_BAR; PG8_MMA(1, 0, At, B0); PG8_MMA(1, 1, At, B1); PG8_BAR; PG8_SCHED;
.LBB0_349:
	ds_read_b128 v[150:153], v169
	ds_read_b128 v[154:157], v169 offset:1024
	ds_read_b128 v[158:161], v169 offset:2048
	ds_read_b128 v[162:165], v169 offset:3072
	ds_read_b128 v[174:177], v170
	ds_read_b128 v[178:181], v170 offset:1024
	ds_read_b128 v[182:185], v170 offset:2048
	ds_read_b128 v[186:189], v170 offset:3072
	s_add_u32 s0, s88, 0xfff00080
	s_addc_u32 s1, s89, -1
	s_cmp_eq_u32 s23, 60
	s_cselect_b32 s93, s51, s1
	s_cselect_b32 s92, s50, s0
	s_cselect_b32 s91, s53, s21
	s_cselect_b32 s90, s52, s9
	ds_read_b128 v[190:193], v171
	ds_read_b128 v[196:199], v171 offset:1024
	ds_read_b128 v[200:203], v171 offset:2048
	ds_read_b128 v[204:207], v171 offset:3072
	ds_read_b128 v[208:211], v171 offset:4096
	ds_read_b128 v[212:215], v171 offset:5120
	ds_read_b128 v[220:223], v171 offset:6144
	ds_read_b128 v[224:227], v171 offset:7168
	s_add_u32 s0, s88, 0xfff00000
	s_addc_u32 s1, s89, -1
	s_add_i32 m0, s27, 0x8000
	s_nop 0
	global_load_lds_dwordx4 v134, s[0:1]
	s_add_i32 m0, s27, 0xa000
	s_nop 0
	global_load_lds_dwordx4 v138, s[0:1]
	s_add_i32 m0, s27, 0xc000
	s_nop 0
	global_load_lds_dwordx4 v134, s[88:89]
	s_add_i32 m0, s27, 0xe000
	s_nop 0
	global_load_lds_dwordx4 v138, s[88:89]
	s_waitcnt lgkmcnt(0)
	s_setprio 1
	v_mfma_f32_16x16x32_bf16 v[38:41], v[150:153], v[190:193], v[38:41]
	v_mfma_f32_16x16x32_bf16 v[38:41], v[154:157], v[196:199], v[38:41]
	v_mfma_f32_16x16x32_bf16 v[130:133], v[150:153], v[200:203], v[130:133]
	v_mfma_f32_16x16x32_bf16 v[130:133], v[154:157], v[204:207], v[130:133]
	v_mfma_f32_16x16x32_bf16 v[114:117], v[150:153], v[208:211], v[114:117]
	v_mfma_f32_16x16x32_bf16 v[114:117], v[154:157], v[212:215], v[114:117]
	v_mfma_f32_16x16x32_bf16 v[98:101], v[150:153], v[220:223], v[98:101]
	v_mfma_f32_16x16x32_bf16 v[98:101], v[154:157], v[224:227], v[98:101]
	v_mfma_f32_16x16x32_bf16 v[94:97], v[158:161], v[220:223], v[94:97]
	v_mfma_f32_16x16x32_bf16 v[94:97], v[162:165], v[224:227], v[94:97]
	v_mfma_f32_16x16x32_bf16 v[110:113], v[158:161], v[208:211], v[110:113]
	v_mfma_f32_16x16x32_bf16 v[110:113], v[162:165], v[212:215], v[110:113]
	v_mfma_f32_16x16x32_bf16 v[126:129], v[158:161], v[200:203], v[126:129]
	v_mfma_f32_16x16x32_bf16 v[126:129], v[162:165], v[204:207], v[126:129]
	v_mfma_f32_16x16x32_bf16 v[30:33], v[158:161], v[190:193], v[30:33]
	v_mfma_f32_16x16x32_bf16 v[30:33], v[162:165], v[196:199], v[30:33]
	v_mfma_f32_16x16x32_bf16 v[50:53], v[174:177], v[190:193], v[50:53]
	v_mfma_f32_16x16x32_bf16 v[50:53], v[178:181], v[196:199], v[50:53]
	v_mfma_f32_16x16x32_bf16 v[122:125], v[174:177], v[200:203], v[122:125]
	v_mfma_f32_16x16x32_bf16 v[122:125], v[178:181], v[204:207], v[122:125]
	v_mfma_f32_16x16x32_bf16 v[106:109], v[174:177], v[208:211], v[106:109]
	v_mfma_f32_16x16x32_bf16 v[106:109], v[178:181], v[212:215], v[106:109]
	v_mfma_f32_16x16x32_bf16 v[90:93], v[174:177], v[220:223], v[90:93]
	v_mfma_f32_16x16x32_bf16 v[90:93], v[178:181], v[224:227], v[90:93]
	v_mfma_f32_16x16x32_bf16 v[86:89], v[182:185], v[220:223], v[86:89]
	v_mfma_f32_16x16x32_bf16 v[86:89], v[186:189], v[224:227], v[86:89]
	v_mfma_f32_16x16x32_bf16 v[102:105], v[182:185], v[208:211], v[102:105]
	v_mfma_f32_16x16x32_bf16 v[102:105], v[186:189], v[212:215], v[102:105]
	v_mfma_f32_16x16x32_bf16 v[118:121], v[182:185], v[200:203], v[118:121]
	v_mfma_f32_16x16x32_bf16 v[118:121], v[186:189], v[204:207], v[118:121]
	v_mfma_f32_16x16x32_bf16 v[46:49], v[182:185], v[190:193], v[46:49]
	v_mfma_f32_16x16x32_bf16 v[46:49], v[186:189], v[196:199], v[46:49]
	s_setprio 0
	s_waitcnt vmcnt(8)
	s_barrier
	ds_read_b128 v[190:193], v171 offset:16384
	ds_read_b128 v[196:199], v171 offset:17408
	ds_read_b128 v[200:203], v171 offset:18432
	ds_read_b128 v[204:207], v171 offset:19456
	ds_read_b128 v[208:211], v171 offset:20480
	ds_read_b128 v[212:215], v171 offset:21504
	ds_read_b128 v[220:223], v171 offset:22528
	ds_read_b128 v[224:227], v171 offset:23552
	s_add_u32 vcc_lo, s90, 0x100000
	s_addc_u32 vcc_hi, s91, 0
	s_add_i32 m0, s27, 0x10000
	s_nop 0
	global_load_lds_dwordx4 v136, s[90:91]
	s_add_i32 m0, s27, 0x12000
	s_nop 0
	global_load_lds_dwordx4 v140, s[90:91]
	s_add_i32 m0, s27, 0x14000
	s_nop 0
	global_load_lds_dwordx4 v136, vcc
	s_add_i32 m0, s27, 0x16000
	s_nop 0
	global_load_lds_dwordx4 v140, vcc
	s_waitcnt lgkmcnt(0)
	s_setprio 1
	v_mfma_f32_16x16x32_bf16 v[82:85], v[150:153], v[190:193], v[82:85]
	v_mfma_f32_16x16x32_bf16 v[82:85], v[154:157], v[196:199], v[82:85]
	v_mfma_f32_16x16x32_bf16 v[66:69], v[150:153], v[200:203], v[66:69]
	v_mfma_f32_16x16x32_bf16 v[66:69], v[154:157], v[204:207], v[66:69]
	v_mfma_f32_16x16x32_bf16 v[42:45], v[150:153], v[208:211], v[42:45]
	v_mfma_f32_16x16x32_bf16 v[42:45], v[154:157], v[212:215], v[42:45]
	v_mfma_f32_16x16x32_bf16 v[18:21], v[150:153], v[220:223], v[18:21]
	v_mfma_f32_16x16x32_bf16 v[18:21], v[154:157], v[224:227], v[18:21]
	v_mfma_f32_16x16x32_bf16 v[14:17], v[158:161], v[220:223], v[14:17]
	v_mfma_f32_16x16x32_bf16 v[14:17], v[162:165], v[224:227], v[14:17]
	v_mfma_f32_16x16x32_bf16 v[34:37], v[158:161], v[208:211], v[34:37]
	v_mfma_f32_16x16x32_bf16 v[34:37], v[162:165], v[212:215], v[34:37]
	v_mfma_f32_16x16x32_bf16 v[62:65], v[158:161], v[200:203], v[62:65]
	v_mfma_f32_16x16x32_bf16 v[62:65], v[162:165], v[204:207], v[62:65]
	v_mfma_f32_16x16x32_bf16 v[78:81], v[158:161], v[190:193], v[78:81]
	v_mfma_f32_16x16x32_bf16 v[78:81], v[162:165], v[196:199], v[78:81]
	v_mfma_f32_16x16x32_bf16 v[74:77], v[174:177], v[190:193], v[74:77]
	v_mfma_f32_16x16x32_bf16 v[74:77], v[178:181], v[196:199], v[74:77]
	v_mfma_f32_16x16x32_bf16 v[58:61], v[174:177], v[200:203], v[58:61]
	v_mfma_f32_16x16x32_bf16 v[58:61], v[178:181], v[204:207], v[58:61]
	v_mfma_f32_16x16x32_bf16 v[26:29], v[174:177], v[208:211], v[26:29]
	v_mfma_f32_16x16x32_bf16 v[26:29], v[178:181], v[212:215], v[26:29]
	v_mfma_f32_16x16x32_bf16 v[10:13], v[174:177], v[220:223], v[10:13]
	v_mfma_f32_16x16x32_bf16 v[10:13], v[178:181], v[224:227], v[10:13]
	v_mfma_f32_16x16x32_bf16 v[4:7], v[182:185], v[220:223], v[6:9]
	v_mfma_f32_16x16x32_bf16 v[4:7], v[186:189], v[224:227], v[4:7]
	v_mfma_f32_16x16x32_bf16 v[22:25], v[182:185], v[208:211], v[22:25]
	v_mfma_f32_16x16x32_bf16 v[22:25], v[186:189], v[212:215], v[22:25]
	v_mfma_f32_16x16x32_bf16 v[54:57], v[182:185], v[200:203], v[54:57]
	v_mfma_f32_16x16x32_bf16 v[54:57], v[186:189], v[204:207], v[54:57]
	v_mfma_f32_16x16x32_bf16 v[70:73], v[182:185], v[190:193], v[70:73]
	v_mfma_f32_16x16x32_bf16 v[70:73], v[186:189], v[196:199], v[70:73]
	s_setprio 0
	s_waitcnt vmcnt(6)
	s_barrier
; #define PG8_STAGE(bufoff, gbase, voff) do { _Pragma("unroll") for (int _i = 0; _i < 2; ++_i) \
;         __builtin_amdgcn_global_load_lds((const unsigned*)((const char*)(gbase) + (voff)[_i]), (PG8_LAS unsigned*)(lds + (bufoff) + ldsw + _i * 8192), 16, 0, 0); } while (0)
; #define PG8_LDA(dst, b, h) do { _Pragma("unroll") for (int m = 0; m < 4; ++m) _Pragma("unroll") for (int k = 0; k < 2; ++k) dst[m][k] = *(const PG8_LAS bf16x8*)(lds + PG8_SA(b, h) + aoff + m * 2048 + k * 1024); } while (0)
; #define PG8_LDB(dst, b, h) do { _Pragma("unroll") for (int n = 0; n < 2; ++n) _Pragma("unroll") for (int k = 0; k < 2; ++k) dst[n][k] = *(const PG8_LAS bf16x8*)(lds + PG8_SB(b, h) + boff + n * 2048 + k * 1024); } while (0)
; #define PG8_MMA(ai, bj, At, Bt) do { __builtin_amdgcn_s_setprio(1); _Pragma("unroll") for (int m = 0; m < 4; ++m) _Pragma("unroll") for (int n = 0; n < 2; ++n) _Pragma("unroll") for (int k = 0; k < 2; ++k) \
;         acc[ai][bj][m][n] = __builtin_amdgcn_mfma_f32_16x16x32_bf16(Bt[n][k], At[m][k], acc[ai][bj][m][n], 0, 0, 0); __builtin_amdgcn_s_setprio(0); } while (0)
; #define PG8_WAIT_V(n) asm volatile("s_waitcnt vmcnt(" #n ")" ::: "memory")
; #define PG8_WAIT_L(n) asm volatile("s_waitcnt lgkmcnt(" #n ")" ::: "memory")
; #define PG8_BAR __builtin_amdgcn_s_barrier()
; #define PG8_SCHED __builtin_amdgcn_sched_barrier(0)
; template <class Epi, class Sched, bool ALIGN_EPI = false, bool SP2 = false>
; __device__ __forceinline__ void gemm_phase(PG8_LAS unsigned char* lds, const Gemm g, const Sched& S, const Epi& E) {
;     ...
;             PG8_LDB(B0, 1, 0); PG8_LDB(B1, 1, 1); PG8_SCHED; PG8_LDA(At, 1, 0); PG8_STAGE(PG8_SA(0, 1), a2 + hstep, voffA);
;             PG8_WAIT_V(8); PG8_WAIT_L(0); PG8_BAR; PG8_MMA(0, 0, At, B0); PG8_MMA(0, 1, At, B1); PG8_BAR; PG8_SCHED;
;             PG8_LDA(At, 1, 1); PG8_STAGE(PG8_SB(1, 0), b3, voffB); PG8_STAGE(PG8_SB(1, 1), b3 + hstep, voffB); PG8_STAGE(PG8_SA(1, 0), a3, voffA);
;             PG8_WAIT_V(8); PG8_WAIT_L(0); PG8_BAR; PG8_MMA(1, 0, At, B0); PG8_MMA(1, 1, At, B1); PG8_BAR; PG8_SCHED;
	s_add_i32 s0, 0, 0x18000
	v_add_u32_e32 v3, s0, v167
	s_add_i32 s1, 0, 0x1c000
	ds_read_b128 v[150:153], v3
	ds_read_b128 v[154:157], v3 offset:1024
	ds_read_b128 v[158:161], v3 offset:2048
	ds_read_b128 v[162:165], v3 offset:3072
	v_add_u32_e32 v3, s1, v167
	ds_read_b128 v[174:177], v3
	ds_read_b128 v[178:181], v3 offset:1024
	ds_read_b128 v[182:185], v3 offset:2048
	ds_read_b128 v[186:189], v3 offset:3072
	ds_read_b128 v[190:193], v171 offset:32768
	ds_read_b128 v[196:199], v171 offset:33792
	ds_read_b128 v[200:203], v171 offset:34816
	ds_read_b128 v[204:207], v171 offset:35840
	ds_read_b128 v[208:211], v171 offset:36864
	ds_read_b128 v[212:215], v171 offset:37888
	ds_read_b128 v[220:223], v171 offset:38912
	ds_read_b128 v[224:227], v171 offset:39936
	s_add_u32 vcc_lo, s92, 0x100000
	s_addc_u32 vcc_hi, s93, 0
	s_mov_b32 m0, s27
	s_nop 0
	global_load_lds_dwordx4 v134, s[92:93]
	s_add_i32 m0, s27, 0x2000
	s_nop 0
	global_load_lds_dwordx4 v138, s[92:93]
	s_add_i32 m0, s27, 0x4000
	s_nop 0
	global_load_lds_dwordx4 v134, vcc
	s_add_i32 m0, s27, 0x6000
	s_nop 0
	global_load_lds_dwordx4 v138, vcc
	s_waitcnt lgkmcnt(0)
	s_setprio 1
	v_mfma_f32_16x16x32_bf16 v[38:41], v[150:153], v[190:193], v[38:41]
	v_mfma_f32_16x16x32_bf16 v[38:41], v[154:157], v[196:199], v[38:41]
	v_mfma_f32_16x16x32_bf16 v[130:133], v[150:153], v[200:203], v[130:133]
	v_mfma_f32_16x16x32_bf16 v[130:133], v[154:157], v[204:207], v[130:133]
	v_mfma_f32_16x16x32_bf16 v[114:117], v[150:153], v[208:211], v[114:117]
	v_mfma_f32_16x16x32_bf16 v[114:117], v[154:157], v[212:215], v[114:117]
	v_mfma_f32_16x16x32_bf16 v[98:101], v[150:153], v[220:223], v[98:101]
	v_mfma_f32_16x16x32_bf16 v[98:101], v[154:157], v[224:227], v[98:101]
	v_mfma_f32_16x16x32_bf16 v[94:97], v[158:161], v[220:223], v[94:97]
	v_mfma_f32_16x16x32_bf16 v[94:97], v[162:165], v[224:227], v[94:97]
	v_mfma_f32_16x16x32_bf16 v[110:113], v[158:161], v[208:211], v[110:113]
	v_mfma_f32_16x16x32_bf16 v[110:113], v[162:165], v[212:215], v[110:113]
	v_mfma_f32_16x16x32_bf16 v[126:129], v[158:161], v[200:203], v[126:129]
	v_mfma_f32_16x16x32_bf16 v[126:129], v[162:165], v[204:207], v[126:129]
	v_mfma_f32_16x16x32_bf16 v[30:33], v[158:161], v[190:193], v[30:33]
	v_mfma_f32_16x16x32_bf16 v[30:33], v[162:165], v[196:199], v[30:33]
	v_mfma_f32_16x16x32_bf16 v[50:53], v[174:177], v[190:193], v[50:53]
	v_mfma_f32_16x16x32_bf16 v[50:53], v[178:181], v[196:199], v[50:53]
	v_mfma_f32_16x16x32_bf16 v[122:125], v[174:177], v[200:203], v[122:125]
	v_mfma_f32_16x16x32_bf16 v[122:125], v[178:181], v[204:207], v[122:125]
	v_mfma_f32_16x16x32_bf16 v[106:109], v[174:177], v[208:211], v[106:109]
	v_mfma_f32_16x16x32_bf16 v[106:109], v[178:181], v[212:215], v[106:109]
	v_mfma_f32_16x16x32_bf16 v[90:93], v[174:177], v[220:223], v[90:93]
	v_mfma_f32_16x16x32_bf16 v[90:93], v[178:181], v[224:227], v[90:93]
	v_mfma_f32_16x16x32_bf16 v[86:89], v[182:185], v[220:223], v[86:89]
	v_mfma_f32_16x16x32_bf16 v[86:89], v[186:189], v[224:227], v[86:89]
	v_mfma_f32_16x16x32_bf16 v[102:105], v[182:185], v[208:211], v[102:105]
	v_mfma_f32_16x16x32_bf16 v[102:105], v[186:189], v[212:215], v[102:105]
	v_mfma_f32_16x16x32_bf16 v[118:121], v[182:185], v[200:203], v[118:121]
	v_mfma_f32_16x16x32_bf16 v[118:121], v[186:189], v[204:207], v[118:121]
	v_mfma_f32_16x16x32_bf16 v[46:49], v[182:185], v[190:193], v[46:49]
	v_mfma_f32_16x16x32_bf16 v[46:49], v[186:189], v[196:199], v[46:49]
	s_setprio 0
	s_waitcnt vmcnt(8)
	s_barrier
	ds_read_b128 v[190:193], v171 offset:49152
	ds_read_b128 v[196:199], v171 offset:50176
	ds_read_b128 v[200:203], v171 offset:51200
	ds_read_b128 v[204:207], v171 offset:52224
	ds_read_b128 v[208:211], v171 offset:53248
	ds_read_b128 v[212:215], v171 offset:54272
	ds_read_b128 v[220:223], v171 offset:55296
	ds_read_b128 v[224:227], v171 offset:56320
	s_add_u32 s0, s90, 0x80
	s_addc_u32 s1, s91, 0
	s_add_u32 vcc_lo, s0, 0x100000
	s_addc_u32 vcc_hi, s1, 0
	s_add_i32 m0, s27, 0x18000
	s_nop 0
	global_load_lds_dwordx4 v136, s[0:1]
	s_add_i32 m0, s27, 0x1a000
	s_nop 0
	global_load_lds_dwordx4 v140, s[0:1]
	s_add_i32 m0, s27, 0x1c000
	s_nop 0
	global_load_lds_dwordx4 v136, vcc
	s_add_i32 m0, s27, 0x1e000
	s_nop 0
	global_load_lds_dwordx4 v140, vcc
	s_waitcnt lgkmcnt(0)
	s_setprio 1
	v_mfma_f32_16x16x32_bf16 v[82:85], v[150:153], v[190:193], v[82:85]
	v_mfma_f32_16x16x32_bf16 v[82:85], v[154:157], v[196:199], v[82:85]
	v_mfma_f32_16x16x32_bf16 v[66:69], v[150:153], v[200:203], v[66:69]
	v_mfma_f32_16x16x32_bf16 v[66:69], v[154:157], v[204:207], v[66:69]
	v_mfma_f32_16x16x32_bf16 v[42:45], v[150:153], v[208:211], v[42:45]
	v_mfma_f32_16x16x32_bf16 v[42:45], v[154:157], v[212:215], v[42:45]
	v_mfma_f32_16x16x32_bf16 v[18:21], v[150:153], v[220:223], v[18:21]
	v_mfma_f32_16x16x32_bf16 v[18:21], v[154:157], v[224:227], v[18:21]
	v_mfma_f32_16x16x32_bf16 v[14:17], v[158:161], v[220:223], v[14:17]
	v_mfma_f32_16x16x32_bf16 v[14:17], v[162:165], v[224:227], v[14:17]
	v_mfma_f32_16x16x32_bf16 v[34:37], v[158:161], v[208:211], v[34:37]
	v_mfma_f32_16x16x32_bf16 v[34:37], v[162:165], v[212:215], v[34:37]
	v_mfma_f32_16x16x32_bf16 v[62:65], v[158:161], v[200:203], v[62:65]
	v_mfma_f32_16x16x32_bf16 v[62:65], v[162:165], v[204:207], v[62:65]
	v_mfma_f32_16x16x32_bf16 v[78:81], v[158:161], v[190:193], v[78:81]
	v_mfma_f32_16x16x32_bf16 v[78:81], v[162:165], v[196:199], v[78:81]
	v_mfma_f32_16x16x32_bf16 v[74:77], v[174:177], v[190:193], v[74:77]
	v_mfma_f32_16x16x32_bf16 v[74:77], v[178:181], v[196:199], v[74:77]
	v_mfma_f32_16x16x32_bf16 v[58:61], v[174:177], v[200:203], v[58:61]
	v_mfma_f32_16x16x32_bf16 v[58:61], v[178:181], v[204:207], v[58:61]
	v_mfma_f32_16x16x32_bf16 v[26:29], v[174:177], v[208:211], v[26:29]
	v_mfma_f32_16x16x32_bf16 v[26:29], v[178:181], v[212:215], v[26:29]
	v_mfma_f32_16x16x32_bf16 v[8:11], v[174:177], v[220:223], v[10:13]
	v_mfma_f32_16x16x32_bf16 v[10:13], v[178:181], v[224:227], v[8:11]
	v_mfma_f32_16x16x32_bf16 v[4:7], v[182:185], v[220:223], v[4:7]
	v_mfma_f32_16x16x32_bf16 v[6:9], v[186:189], v[224:227], v[4:7]
	v_mfma_f32_16x16x32_bf16 v[22:25], v[182:185], v[208:211], v[22:25]
	v_mfma_f32_16x16x32_bf16 v[22:25], v[186:189], v[212:215], v[22:25]
	v_mfma_f32_16x16x32_bf16 v[54:57], v[182:185], v[200:203], v[54:57]
	v_mfma_f32_16x16x32_bf16 v[54:57], v[186:189], v[204:207], v[54:57]
	v_mfma_f32_16x16x32_bf16 v[70:73], v[182:185], v[190:193], v[70:73]
	v_mfma_f32_16x16x32_bf16 v[70:73], v[186:189], v[196:199], v[70:73]
	s_setprio 0
	s_waitcnt vmcnt(6)
	s_barrier
	s_add_i32 s23, s23, 2
	s_add_u32 s88, s88, 0x100
	s_addc_u32 s89, s89, 0
	s_add_u32 s9, s9, 0x100
	s_addc_u32 s21, s21, 0
	s_cmp_gt_u32 s23, 61
	s_cbranch_scc0 .LBB0_349
	s_branch .Lip_exit
; #define PG8_STAGE(bufoff, gbase, voff) do { _Pragma("unroll") for (int _i = 0; _i < 2; ++_i) \
;         __builtin_amdgcn_global_load_lds((const unsigned*)((const char*)(gbase) + (voff)[_i]), (PG8_LAS unsigned*)(lds + (bufoff) + ldsw + _i * 8192), 16, 0, 0); } while (0)
; #define PG8_LDA(dst, b, h) do { _Pragma("unroll") for (int m = 0; m < 4; ++m) _Pragma("unroll") for (int k = 0; k < 2; ++k) dst[m][k] = *(const PG8_LAS bf16x8*)(lds + PG8_SA(b, h) + aoff + m * 2048 + k * 1024); } while (0)
; #define PG8_LDB(dst, b, h) do { _Pragma("unroll") for (int n = 0; n < 2; ++n) _Pragma("unroll") for (int k = 0; k < 2; ++k) dst[n][k] = *(const PG8_LAS bf16x8*)(lds + PG8_SB(b, h) + boff + n * 2048 + k * 1024); } while (0)
; #define PG8_MMA(ai, bj, At, Bt) do { __builtin_amdgcn_s_setprio(1); _Pragma("unroll") for (int m = 0; m < 4; ++m) _Pragma("unroll") for (int n = 0; n < 2; ++n) _Pragma("unroll") for (int k = 0; k < 2; ++k) \
;         acc[ai][bj][m][n] = __builtin_amdgcn_mfma_f32_16x16x32_bf16(Bt[n][k], At[m][k], acc[ai][bj][m][n], 0, 0, 0); __builtin_amdgcn_s_setprio(0); } while (0)
; #define PG8_BAR __builtin_amdgcn_s_barrier()
; template <class Epi, class Sched, bool ALIGN_EPI = false, bool SP2 = false>
; __device__ __forceinline__ void gemm_phase(PG8_LAS unsigned char* lds, const Gemm g, const Sched& S, const Epi& E) {
;     ...
;             const bool last = (t == nt - 2);
;             const char* a1 = cA + (size_t)(t + 1) * kstep;
;             const char* a2 = last ? nA : cA + (size_t)(t + 2) * kstep; const char* b2 = last ? nB : cB + (size_t)(t + 2) * kstep;
;             const char* a3 = a2 + kstep; const char* b3 = b2 + kstep;
;             if (last && has_next) S.a_ready(nxt);
;             if constexpr (Epi::MIDK) { if (t == (nt >> 1)) { E.midk(acc, wr, fr); asm volatile("s_waitcnt lgkmcnt(0)" ::: "memory"); } }
;             if constexpr (SP2) {
;             PG8_LDB(B0, 0, 0); PG8_LDB(B1, 0, 1); PG8_SCHED; PG8_LDA(At, 0, 0); PG8_STAGE(PG8_SA(1, 1), a1 + hstep, voffA);
;             PG8_WAIT_V(8); PG8_WAIT_L(0); PG8_BAR; PG8_MMA(0, 0, At, B0); PG8_MMA(0, 1, At, B1); PG8_BAR; PG8_SCHED;
;             PG8_LDA(At, 0, 1); PG8_STAGE(PG8_SB(0, 0), b2, voffB); PG8_STAGE(PG8_SB(0, 1), b2 + hstep, voffB); PG8_STAGE(PG8_SA(0, 0), a2, voffA);
;             PG8_WAIT_V(8); PG8_WAIT_L(0); PG8_BAR; PG8_MMA(1, 0, At, B0); PG8_MMA(1, 1, At, B1); PG8_BAR; PG8_SCHED;
.Lip_h1:
	ds_read_b128 v[150:153], v169
	ds_read_b128 v[154:157], v169 offset:1024
	ds_read_b128 v[158:161], v169 offset:2048
	ds_read_b128 v[162:165], v169 offset:3072
	ds_read_b128 v[174:177], v170
	ds_read_b128 v[178:181], v170 offset:1024
	ds_read_b128 v[182:185], v170 offset:2048
	ds_read_b128 v[186:189], v170 offset:3072
	s_add_u32 s0, s88, 0xfff00080
	s_addc_u32 s1, s89, -1
	s_cmp_eq_u32 s23, 60
	s_cselect_b32 s93, s51, s1
	s_cselect_b32 s92, s50, s0
	s_cselect_b32 s91, s53, s21
	s_cselect_b32 s90, s52, s9
	ds_read_b128 v[190:193], v171
	ds_read_b128 v[196:199], v171 offset:1024
	ds_read_b128 v[200:203], v171 offset:2048
	ds_read_b128 v[204:207], v171 offset:3072
	ds_read_b128 v[208:211], v171 offset:4096
	ds_read_b128 v[212:215], v171 offset:5120
	ds_read_b128 v[220:223], v171 offset:6144
	ds_read_b128 v[224:227], v171 offset:7168
	s_add_u32 s0, s88, 0xfff00000
	s_addc_u32 s1, s89, -1
	s_add_i32 m0, s27, 0x8000
	s_nop 0
	global_load_lds_dwordx4 v134, s[0:1]
	s_add_i32 m0, s27, 0xa000
	s_nop 0
	global_load_lds_dwordx4 v138, s[0:1]
	s_add_i32 m0, s27, 0xc000
	s_nop 0
	global_load_lds_dwordx4 v134, s[88:89]
	s_add_i32 m0, s27, 0xe000
	s_nop 0
	global_load_lds_dwordx4 v138, s[88:89]
	s_sleep 2
	s_waitcnt lgkmcnt(0)
	s_waitcnt vmcnt(8)
	s_barrier
	s_setprio 2
	v_mfma_f32_16x16x32_bf16 v[38:41], v[150:153], v[190:193], v[38:41]
	v_mfma_f32_16x16x32_bf16 v[38:41], v[154:157], v[196:199], v[38:41]
	v_mfma_f32_16x16x32_bf16 v[130:133], v[150:153], v[200:203], v[130:133]
	v_mfma_f32_16x16x32_bf16 v[130:133], v[154:157], v[204:207], v[130:133]
	v_mfma_f32_16x16x32_bf16 v[114:117], v[150:153], v[208:211], v[114:117]
	v_mfma_f32_16x16x32_bf16 v[114:117], v[154:157], v[212:215], v[114:117]
	v_mfma_f32_16x16x32_bf16 v[98:101], v[150:153], v[220:223], v[98:101]
	v_mfma_f32_16x16x32_bf16 v[98:101], v[154:157], v[224:227], v[98:101]
	v_mfma_f32_16x16x32_bf16 v[94:97], v[158:161], v[220:223], v[94:97]
	v_mfma_f32_16x16x32_bf16 v[94:97], v[162:165], v[224:227], v[94:97]
	v_mfma_f32_16x16x32_bf16 v[110:113], v[158:161], v[208:211], v[110:113]
	v_mfma_f32_16x16x32_bf16 v[110:113], v[162:165], v[212:215], v[110:113]
	v_mfma_f32_16x16x32_bf16 v[126:129], v[158:161], v[200:203], v[126:129]
	v_mfma_f32_16x16x32_bf16 v[126:129], v[162:165], v[204:207], v[126:129]
	v_mfma_f32_16x16x32_bf16 v[30:33], v[158:161], v[190:193], v[30:33]
	v_mfma_f32_16x16x32_bf16 v[30:33], v[162:165], v[196:199], v[30:33]
	v_mfma_f32_16x16x32_bf16 v[50:53], v[174:177], v[190:193], v[50:53]
	v_mfma_f32_16x16x32_bf16 v[50:53], v[178:181], v[196:199], v[50:53]
	v_mfma_f32_16x16x32_bf16 v[122:125], v[174:177], v[200:203], v[122:125]
	v_mfma_f32_16x16x32_bf16 v[122:125], v[178:181], v[204:207], v[122:125]
	v_mfma_f32_16x16x32_bf16 v[106:109], v[174:177], v[208:211], v[106:109]
	v_mfma_f32_16x16x32_bf16 v[106:109], v[178:181], v[212:215], v[106:109]
	v_mfma_f32_16x16x32_bf16 v[90:93], v[174:177], v[220:223], v[90:93]
	v_mfma_f32_16x16x32_bf16 v[90:93], v[178:181], v[224:227], v[90:93]
	v_mfma_f32_16x16x32_bf16 v[86:89], v[182:185], v[220:223], v[86:89]
	v_mfma_f32_16x16x32_bf16 v[86:89], v[186:189], v[224:227], v[86:89]
	v_mfma_f32_16x16x32_bf16 v[102:105], v[182:185], v[208:211], v[102:105]
	v_mfma_f32_16x16x32_bf16 v[102:105], v[186:189], v[212:215], v[102:105]
	v_mfma_f32_16x16x32_bf16 v[118:121], v[182:185], v[200:203], v[118:121]
	v_mfma_f32_16x16x32_bf16 v[118:121], v[186:189], v[204:207], v[118:121]
	v_mfma_f32_16x16x32_bf16 v[46:49], v[182:185], v[190:193], v[46:49]
	v_mfma_f32_16x16x32_bf16 v[46:49], v[186:189], v[196:199], v[46:49]
	s_setprio 0
	ds_read_b128 v[190:193], v171 offset:16384
	ds_read_b128 v[196:199], v171 offset:17408
	ds_read_b128 v[200:203], v171 offset:18432
	ds_read_b128 v[204:207], v171 offset:19456
	ds_read_b128 v[208:211], v171 offset:20480
	ds_read_b128 v[212:215], v171 offset:21504
	ds_read_b128 v[220:223], v171 offset:22528
	ds_read_b128 v[224:227], v171 offset:23552
	s_add_u32 vcc_lo, s90, 0x100000
	s_addc_u32 vcc_hi, s91, 0
	s_add_i32 m0, s27, 0x10000
	s_nop 0
	global_load_lds_dwordx4 v136, s[90:91]
	s_add_i32 m0, s27, 0x12000
	s_nop 0
	global_load_lds_dwordx4 v140, s[90:91]
	s_add_i32 m0, s27, 0x14000
	s_nop 0
	global_load_lds_dwordx4 v136, vcc
	s_add_i32 m0, s27, 0x16000
	s_nop 0
	global_load_lds_dwordx4 v140, vcc
	s_sleep 2
	s_waitcnt lgkmcnt(0)
	s_waitcnt vmcnt(6)
	s_barrier
; #define PG8_STAGE(bufoff, gbase, voff) do { _Pragma("unroll") for (int _i = 0; _i < 2; ++_i) \
;         __builtin_amdgcn_global_load_lds((const unsigned*)((const char*)(gbase) + (voff)[_i]), (PG8_LAS unsigned*)(lds + (bufoff) + ldsw + _i * 8192), 16, 0, 0); } while (0)
; #define PG8_LDA(dst, b, h) do { _Pragma("unroll") for (int m = 0; m < 4; ++m) _Pragma("unroll") for (int k = 0; k < 2; ++k) dst[m][k] = *(const PG8_LAS bf16x8*)(lds + PG8_SA(b, h) + aoff + m * 2048 + k * 1024); } while (0)
; #define PG8_LDB(dst, b, h) do { _Pragma("unroll") for (int n = 0; n < 2; ++n) _Pragma("unroll") for (int k = 0; k < 2; ++k) dst[n][k] = *(const PG8_LAS bf16x8*)(lds + PG8_SB(b, h) + boff + n * 2048 + k * 1024); } while (0)
; #define PG8_MMA(ai, bj, At, Bt) do { __builtin_amdgcn_s_setprio(1); _Pragma("unroll") for (int m = 0; m < 4; ++m) _Pragma("unroll") for (int n = 0; n < 2; ++n) _Pragma("unroll") for (int k = 0; k < 2; ++k) \
;         acc[ai][bj][m][n] = __builtin_amdgcn_mfma_f32_16x16x32_bf16(Bt[n][k], At[m][k], acc[ai][bj][m][n], 0, 0, 0); __builtin_amdgcn_s_setprio(0); } while (0)
; #define PG8_WAIT_V(n) asm volatile("s_waitcnt vmcnt(" #n ")" ::: "memory")
; #define PG8_WAIT_L(n) asm volatile("s_waitcnt lgkmcnt(" #n ")" ::: "memory")
; #define PG8_BAR __builtin_amdgcn_s_barrier()
; #define PG8_SCHED __builtin_amdgcn_sched_barrier(0)
; template <class Epi, class Sched, bool ALIGN_EPI = false, bool SP2 = false>
; __device__ __forceinline__ void gemm_phase(PG8_LAS unsigned char* lds, const Gemm g, const Sched& S, const Epi& E) {
;     ...
;             PG8_LDA(At, 0, 1); PG8_STAGE(PG8_SB(0, 0), b2, voffB); PG8_STAGE(PG8_SB(0, 1), b2 + hstep, voffB); PG8_STAGE(PG8_SA(0, 0), a2, voffA);
;             PG8_WAIT_V(8); PG8_WAIT_L(0); PG8_BAR; PG8_MMA(1, 0, At, B0); PG8_MMA(1, 1, At, B1); PG8_BAR; PG8_SCHED;
;             PG8_LDB(B0, 1, 0); PG8_LDB(B1, 1, 1); PG8_SCHED; PG8_LDA(At, 1, 0); PG8_STAGE(PG8_SA(0, 1), a2 + hstep, voffA);
;             PG8_WAIT_V(8); PG8_WAIT_L(0); PG8_BAR; PG8_MMA(0, 0, At, B0); PG8_MMA(0, 1, At, B1); PG8_BAR; PG8_SCHED;
	s_setprio 2
	v_mfma_f32_16x16x32_bf16 v[82:85], v[150:153], v[190:193], v[82:85]
	v_mfma_f32_16x16x32_bf16 v[82:85], v[154:157], v[196:199], v[82:85]
	v_mfma_f32_16x16x32_bf16 v[66:69], v[150:153], v[200:203], v[66:69]
	v_mfma_f32_16x16x32_bf16 v[66:69], v[154:157], v[204:207], v[66:69]
	v_mfma_f32_16x16x32_bf16 v[42:45], v[150:153], v[208:211], v[42:45]
	v_mfma_f32_16x16x32_bf16 v[42:45], v[154:157], v[212:215], v[42:45]
	v_mfma_f32_16x16x32_bf16 v[18:21], v[150:153], v[220:223], v[18:21]
	v_mfma_f32_16x16x32_bf16 v[18:21], v[154:157], v[224:227], v[18:21]
	v_mfma_f32_16x16x32_bf16 v[14:17], v[158:161], v[220:223], v[14:17]
	v_mfma_f32_16x16x32_bf16 v[14:17], v[162:165], v[224:227], v[14:17]
	v_mfma_f32_16x16x32_bf16 v[34:37], v[158:161], v[208:211], v[34:37]
	v_mfma_f32_16x16x32_bf16 v[34:37], v[162:165], v[212:215], v[34:37]
	v_mfma_f32_16x16x32_bf16 v[62:65], v[158:161], v[200:203], v[62:65]
	v_mfma_f32_16x16x32_bf16 v[62:65], v[162:165], v[204:207], v[62:65]
	v_mfma_f32_16x16x32_bf16 v[78:81], v[158:161], v[190:193], v[78:81]
	v_mfma_f32_16x16x32_bf16 v[78:81], v[162:165], v[196:199], v[78:81]
	v_mfma_f32_16x16x32_bf16 v[74:77], v[174:177], v[190:193], v[74:77]
	v_mfma_f32_16x16x32_bf16 v[74:77], v[178:181], v[196:199], v[74:77]
	v_mfma_f32_16x16x32_bf16 v[58:61], v[174:177], v[200:203], v[58:61]
	v_mfma_f32_16x16x32_bf16 v[58:61], v[178:181], v[204:207], v[58:61]
	v_mfma_f32_16x16x32_bf16 v[26:29], v[174:177], v[208:211], v[26:29]
	v_mfma_f32_16x16x32_bf16 v[26:29], v[178:181], v[212:215], v[26:29]
	v_mfma_f32_16x16x32_bf16 v[10:13], v[174:177], v[220:223], v[10:13]
	v_mfma_f32_16x16x32_bf16 v[10:13], v[178:181], v[224:227], v[10:13]
	v_mfma_f32_16x16x32_bf16 v[4:7], v[182:185], v[220:223], v[6:9]
	v_mfma_f32_16x16x32_bf16 v[4:7], v[186:189], v[224:227], v[4:7]
	v_mfma_f32_16x16x32_bf16 v[22:25], v[182:185], v[208:211], v[22:25]
	v_mfma_f32_16x16x32_bf16 v[22:25], v[186:189], v[212:215], v[22:25]
	v_mfma_f32_16x16x32_bf16 v[54:57], v[182:185], v[200:203], v[54:57]
	v_mfma_f32_16x16x32_bf16 v[54:57], v[186:189], v[204:207], v[54:57]
	v_mfma_f32_16x16x32_bf16 v[70:73], v[182:185], v[190:193], v[70:73]
	v_mfma_f32_16x16x32_bf16 v[70:73], v[186:189], v[196:199], v[70:73]
	s_setprio 0
	s_add_i32 s0, 0, 0x18000
	v_add_u32_e32 v3, s0, v167
	s_add_i32 s1, 0, 0x1c000
	ds_read_b128 v[150:153], v3
	ds_read_b128 v[154:157], v3 offset:1024
	ds_read_b128 v[158:161], v3 offset:2048
	ds_read_b128 v[162:165], v3 offset:3072
	v_add_u32_e32 v3, s1, v167
	ds_read_b128 v[174:177], v3
	ds_read_b128 v[178:181], v3 offset:1024
	ds_read_b128 v[182:185], v3 offset:2048
	ds_read_b128 v[186:189], v3 offset:3072
	ds_read_b128 v[190:193], v171 offset:32768
	ds_read_b128 v[196:199], v171 offset:33792
	ds_read_b128 v[200:203], v171 offset:34816
	ds_read_b128 v[204:207], v171 offset:35840
	ds_read_b128 v[208:211], v171 offset:36864
	ds_read_b128 v[212:215], v171 offset:37888
	ds_read_b128 v[220:223], v171 offset:38912
	ds_read_b128 v[224:227], v171 offset:39936
	s_add_u32 vcc_lo, s92, 0x100000
	s_addc_u32 vcc_hi, s93, 0
	s_mov_b32 m0, s27
	s_nop 0
	global_load_lds_dwordx4 v134, s[92:93]
	s_add_i32 m0, s27, 0x2000
	s_nop 0
	global_load_lds_dwordx4 v138, s[92:93]
	s_add_i32 m0, s27, 0x4000
	s_nop 0
	global_load_lds_dwordx4 v134, vcc
	s_add_i32 m0, s27, 0x6000
	s_nop 0
	global_load_lds_dwordx4 v138, vcc
	s_sleep 2
	s_waitcnt lgkmcnt(0)
	s_waitcnt vmcnt(8)
	s_barrier
; #define PG8_STAGE(bufoff, gbase, voff) do { _Pragma("unroll") for (int _i = 0; _i < 2; ++_i) \
;         __builtin_amdgcn_global_load_lds((const unsigned*)((const char*)(gbase) + (voff)[_i]), (PG8_LAS unsigned*)(lds + (bufoff) + ldsw + _i * 8192), 16, 0, 0); } while (0)
; #define PG8_LDA(dst, b, h) do { _Pragma("unroll") for (int m = 0; m < 4; ++m) _Pragma("unroll") for (int k = 0; k < 2; ++k) dst[m][k] = *(const PG8_LAS bf16x8*)(lds + PG8_SA(b, h) + aoff + m * 2048 + k * 1024); } while (0)
; #define PG8_LDB(dst, b, h) do { _Pragma("unroll") for (int n = 0; n < 2; ++n) _Pragma("unroll") for (int k = 0; k < 2; ++k) dst[n][k] = *(const PG8_LAS bf16x8*)(lds + PG8_SB(b, h) + boff + n * 2048 + k * 1024); } while (0)
; #define PG8_MMA(ai, bj, At, Bt) do { __builtin_amdgcn_s_setprio(1); _Pragma("unroll") for (int m = 0; m < 4; ++m) _Pragma("unroll") for (int n = 0; n < 2; ++n) _Pragma("unroll") for (int k = 0; k < 2; ++k) \
;         acc[ai][bj][m][n] = __builtin_amdgcn_mfma_f32_16x16x32_bf16(Bt[n][k], At[m][k], acc[ai][bj][m][n], 0, 0, 0); __builtin_amdgcn_s_setprio(0); } while (0)
; #define PG8_WAIT_V(n) asm volatile("s_waitcnt vmcnt(" #n ")" ::: "memory")
; #define PG8_WAIT_L(n) asm volatile("s_waitcnt lgkmcnt(" #n ")" ::: "memory")
; #define PG8_BAR __builtin_amdgcn_s_barrier()
; #define PG8_SCHED __builtin_amdgcn_sched_barrier(0)
; template <class Epi, class Sched, bool ALIGN_EPI = false, bool SP2 = false>
; __device__ __forceinline__ void gemm_phase(PG8_LAS unsigned char* lds, const Gemm g, const Sched& S, const Epi& E) {
;     ...
;             PG8_LDB(B0, 1, 0); PG8_LDB(B1, 1, 1); PG8_SCHED; PG8_LDA(At, 1, 0); PG8_STAGE(PG8_SA(0, 1), a2 + hstep, voffA);
;             PG8_WAIT_V(8); PG8_WAIT_L(0); PG8_BAR; PG8_MMA(0, 0, At, B0); PG8_MMA(0, 1, At, B1); PG8_BAR; PG8_SCHED;
;             PG8_LDA(At, 1, 1); PG8_STAGE(PG8_SB(1, 0), b3, voffB); PG8_STAGE(PG8_SB(1, 1), b3 + hstep, voffB); PG8_STAGE(PG8_SA(1, 0), a3, voffA);
;             PG8_WAIT_V(8); PG8_WAIT_L(0); PG8_BAR; PG8_MMA(1, 0, At, B0); PG8_MMA(1, 1, At, B1); PG8_BAR; PG8_SCHED;
	s_setprio 2
	v_mfma_f32_16x16x32_bf16 v[38:41], v[150:153], v[190:193], v[38:41]
	v_mfma_f32_16x16x32_bf16 v[38:41], v[154:157], v[196:199], v[38:41]
	v_mfma_f32_16x16x32_bf16 v[130:133], v[150:153], v[200:203], v[130:133]
	v_mfma_f32_16x16x32_bf16 v[130:133], v[154:157], v[204:207], v[130:133]
	v_mfma_f32_16x16x32_bf16 v[114:117], v[150:153], v[208:211], v[114:117]
	v_mfma_f32_16x16x32_bf16 v[114:117], v[154:157], v[212:215], v[114:117]
	v_mfma_f32_16x16x32_bf16 v[98:101], v[150:153], v[220:223], v[98:101]
	v_mfma_f32_16x16x32_bf16 v[98:101], v[154:157], v[224:227], v[98:101]
	v_mfma_f32_16x16x32_bf16 v[94:97], v[158:161], v[220:223], v[94:97]
	v_mfma_f32_16x16x32_bf16 v[94:97], v[162:165], v[224:227], v[94:97]
	v_mfma_f32_16x16x32_bf16 v[110:113], v[158:161], v[208:211], v[110:113]
	v_mfma_f32_16x16x32_bf16 v[110:113], v[162:165], v[212:215], v[110:113]
	v_mfma_f32_16x16x32_bf16 v[126:129], v[158:161], v[200:203], v[126:129]
	v_mfma_f32_16x16x32_bf16 v[126:129], v[162:165], v[204:207], v[126:129]
	v_mfma_f32_16x16x32_bf16 v[30:33], v[158:161], v[190:193], v[30:33]
	v_mfma_f32_16x16x32_bf16 v[30:33], v[162:165], v[196:199], v[30:33]
	v_mfma_f32_16x16x32_bf16 v[50:53], v[174:177], v[190:193], v[50:53]
	v_mfma_f32_16x16x32_bf16 v[50:53], v[178:181], v[196:199], v[50:53]
	v_mfma_f32_16x16x32_bf16 v[122:125], v[174:177], v[200:203], v[122:125]
	v_mfma_f32_16x16x32_bf16 v[122:125], v[178:181], v[204:207], v[122:125]
	v_mfma_f32_16x16x32_bf16 v[106:109], v[174:177], v[208:211], v[106:109]
	v_mfma_f32_16x16x32_bf16 v[106:109], v[178:181], v[212:215], v[106:109]
	v_mfma_f32_16x16x32_bf16 v[90:93], v[174:177], v[220:223], v[90:93]
	v_mfma_f32_16x16x32_bf16 v[90:93], v[178:181], v[224:227], v[90:93]
	v_mfma_f32_16x16x32_bf16 v[86:89], v[182:185], v[220:223], v[86:89]
	v_mfma_f32_16x16x32_bf16 v[86:89], v[186:189], v[224:227], v[86:89]
	v_mfma_f32_16x16x32_bf16 v[102:105], v[182:185], v[208:211], v[102:105]
	v_mfma_f32_16x16x32_bf16 v[102:105], v[186:189], v[212:215], v[102:105]
	v_mfma_f32_16x16x32_bf16 v[118:121], v[182:185], v[200:203], v[118:121]
	v_mfma_f32_16x16x32_bf16 v[118:121], v[186:189], v[204:207], v[118:121]
	v_mfma_f32_16x16x32_bf16 v[46:49], v[182:185], v[190:193], v[46:49]
	v_mfma_f32_16x16x32_bf16 v[46:49], v[186:189], v[196:199], v[46:49]
	s_setprio 0
	ds_read_b128 v[190:193], v171 offset:49152
	ds_read_b128 v[196:199], v171 offset:50176
	ds_read_b128 v[200:203], v171 offset:51200
	ds_read_b128 v[204:207], v171 offset:52224
	ds_read_b128 v[208:211], v171 offset:53248
	ds_read_b128 v[212:215], v171 offset:54272
	ds_read_b128 v[220:223], v171 offset:55296
	ds_read_b128 v[224:227], v171 offset:56320
	s_add_u32 s0, s90, 0x80
	s_addc_u32 s1, s91, 0
	s_add_u32 vcc_lo, s0, 0x100000
	s_addc_u32 vcc_hi, s1, 0
	s_add_i32 m0, s27, 0x18000
	s_nop 0
	global_load_lds_dwordx4 v136, s[0:1]
	s_add_i32 m0, s27, 0x1a000
	s_nop 0
	global_load_lds_dwordx4 v140, s[0:1]
	s_add_i32 m0, s27, 0x1c000
	s_nop 0
	global_load_lds_dwordx4 v136, vcc
	s_add_i32 m0, s27, 0x1e000
	s_nop 0
	global_load_lds_dwordx4 v140, vcc
	s_sleep 2
	s_waitcnt lgkmcnt(0)
	s_waitcnt vmcnt(6)
	s_barrier
	s_setprio 2
	v_mfma_f32_16x16x32_bf16 v[82:85], v[150:153], v[190:193], v[82:85]
	v_mfma_f32_16x16x32_bf16 v[82:85], v[154:157], v[196:199], v[82:85]
	v_mfma_f32_16x16x32_bf16 v[66:69], v[150:153], v[200:203], v[66:69]
	v_mfma_f32_16x16x32_bf16 v[66:69], v[154:157], v[204:207], v[66:69]
	v_mfma_f32_16x16x32_bf16 v[42:45], v[150:153], v[208:211], v[42:45]
	v_mfma_f32_16x16x32_bf16 v[42:45], v[154:157], v[212:215], v[42:45]
	v_mfma_f32_16x16x32_bf16 v[18:21], v[150:153], v[220:223], v[18:21]
	v_mfma_f32_16x16x32_bf16 v[18:21], v[154:157], v[224:227], v[18:21]
	v_mfma_f32_16x16x32_bf16 v[14:17], v[158:161], v[220:223], v[14:17]
	v_mfma_f32_16x16x32_bf16 v[14:17], v[162:165], v[224:227], v[14:17]
	v_mfma_f32_16x16x32_bf16 v[34:37], v[158:161], v[208:211], v[34:37]
	v_mfma_f32_16x16x32_bf16 v[34:37], v[162:165], v[212:215], v[34:37]
	v_mfma_f32_16x16x32_bf16 v[62:65], v[158:161], v[200:203], v[62:65]
	v_mfma_f32_16x16x32_bf16 v[62:65], v[162:165], v[204:207], v[62:65]
	v_mfma_f32_16x16x32_bf16 v[78:81], v[158:161], v[190:193], v[78:81]
	v_mfma_f32_16x16x32_bf16 v[78:81], v[162:165], v[196:199], v[78:81]
	v_mfma_f32_16x16x32_bf16 v[74:77], v[174:177], v[190:193], v[74:77]
	v_mfma_f32_16x16x32_bf16 v[74:77], v[178:181], v[196:199], v[74:77]
	v_mfma_f32_16x16x32_bf16 v[58:61], v[174:177], v[200:203], v[58:61]
	v_mfma_f32_16x16x32_bf16 v[58:61], v[178:181], v[204:207], v[58:61]
	v_mfma_f32_16x16x32_bf16 v[26:29], v[174:177], v[208:211], v[26:29]
	v_mfma_f32_16x16x32_bf16 v[26:29], v[178:181], v[212:215], v[26:29]
	v_mfma_f32_16x16x32_bf16 v[8:11], v[174:177], v[220:223], v[10:13]
	v_mfma_f32_16x16x32_bf16 v[10:13], v[178:181], v[224:227], v[8:11]
	v_mfma_f32_16x16x32_bf16 v[4:7], v[182:185], v[220:223], v[4:7]
	v_mfma_f32_16x16x32_bf16 v[6:9], v[186:189], v[224:227], v[4:7]
	v_mfma_f32_16x16x32_bf16 v[22:25], v[182:185], v[208:211], v[22:25]
	v_mfma_f32_16x16x32_bf16 v[22:25], v[186:189], v[212:215], v[22:25]
	v_mfma_f32_16x16x32_bf16 v[54:57], v[182:185], v[200:203], v[54:57]
	v_mfma_f32_16x16x32_bf16 v[54:57], v[186:189], v[204:207], v[54:57]
	v_mfma_f32_16x16x32_bf16 v[70:73], v[182:185], v[190:193], v[70:73]
	v_mfma_f32_16x16x32_bf16 v[70:73], v[186:189], v[196:199], v[70:73]
	s_setprio 0
	s_add_i32 s23, s23, 2
	s_add_u32 s88, s88, 0x100
	s_addc_u32 s89, s89, 0
	s_add_u32 s9, s9, 0x100
	s_addc_u32 s21, s21, 0
	s_cmp_gt_u32 s23, 61
	s_cbranch_scc0 .Lip_h1

; #define PG8_STAGE(bufoff, gbase, voff) do { _Pragma("unroll") for (int _i = 0; _i < 2; ++_i) \
;         __builtin_amdgcn_global_load_lds((const unsigned*)((const char*)(gbase) + (voff)[_i]), (PG8_LAS unsigned*)(lds + (bufoff) + ldsw + _i * 8192), 16, 0, 0); } while (0)
; #define PG8_LDA(dst, b, h) do { _Pragma("unroll") for (int m = 0; m < 4; ++m) _Pragma("unroll") for (int k = 0; k < 2; ++k) dst[m][k] = *(const PG8_LAS bf16x8*)(lds + PG8_SA(b, h) + aoff + m * 2048 + k * 1024); } while (0)
; #define PG8_LDB(dst, b, h) do { _Pragma("unroll") for (int n = 0; n < 2; ++n) _Pragma("unroll") for (int k = 0; k < 2; ++k) dst[n][k] = *(const PG8_LAS bf16x8*)(lds + PG8_SB(b, h) + boff + n * 2048 + k * 1024); } while (0)
; #define PG8_MMA(ai, bj, At, Bt) do { __builtin_amdgcn_s_setprio(1); _Pragma("unroll") for (int m = 0; m < 4; ++m) _Pragma("unroll") for (int n = 0; n < 2; ++n) _Pragma("unroll") for (int k = 0; k < 2; ++k) \
;         acc[ai][bj][m][n] = __builtin_amdgcn_mfma_f32_16x16x32_bf16(Bt[n][k], At[m][k], acc[ai][bj][m][n], 0, 0, 0); __builtin_amdgcn_s_setprio(0); } while (0)
; #define PG8_WAIT_V(n) asm volatile("s_waitcnt vmcnt(" #n ")" ::: "memory")
; #define PG8_BAR __builtin_amdgcn_s_barrier()
; template <class Epi, class Sched, bool ALIGN_EPI = false, bool SP2 = false>
; __device__ __forceinline__ void gemm_phase(PG8_LAS unsigned char* lds, const Gemm g, const Sched& S, const Epi& E) {
;     ...
;         for (int t = 0; t < nt; t += 2) {
;             const bool last = (t == nt - 2);
;             const char* a1 = cA + (size_t)(t + 1) * kstep;
;             const char* a2 = last ? nA : cA + (size_t)(t + 2) * kstep; const char* b2 = last ? nB : cB + (size_t)(t + 2) * kstep;
;             const char* a3 = a2 + kstep; const char* b3 = b2 + kstep;
;             if (last && has_next) S.a_ready(nxt);
;             if constexpr (Epi::MIDK) { if (t == (nt >> 1)) { E.midk(acc, wr, fr); asm volatile("s_waitcnt lgkmcnt(0)" ::: "memory"); } }
;             if constexpr (SP2) {
;             PG8_LDB(B0, 0, 0); PG8_LDB(B1, 0, 1); PG8_SCHED; PG8_LDA(At, 0, 0); PG8_STAGE(PG8_SA(1, 1), a1 + hstep, voffA);
;             PG8_WAIT_V(8); PG8_WAIT_L(0); PG8_BAR; PG8_MMA(0, 0, At, B0); PG8_MMA(0, 1, At, B1); PG8_BAR; PG8_SCHED;
;             PG8_LDA(At, 0, 1); PG8_STAGE(PG8_SB(0, 0), b2, voffB); PG8_STAGE(PG8_SB(0, 1), b2 + hstep, voffB); PG8_STAGE(PG8_SA(0, 0), a2, voffA);
.LBB0_911:
	v_add_u32_e32 v3, s83, v219
	ds_read_b128 v[98:101], v3
	ds_read_b128 v[102:105], v3 offset:1024
	ds_read_b128 v[106:109], v3 offset:2048
	ds_read_b128 v[166:169], v3 offset:3072
	v_add_u32_e32 v3, s86, v219
	s_add_u32 s62, s58, s60
	ds_read_b128 v[170:173], v3
	ds_read_b128 v[174:177], v3 offset:1024
	ds_read_b128 v[178:181], v3 offset:2048
	ds_read_b128 v[182:185], v3 offset:3072
	s_addc_u32 s63, s59, s61
	s_add_u32 s62, s62, 0x100
	s_addc_u32 s63, s63, 0
	s_add_u32 s93, s90, s60
	s_addc_u32 s94, s91, s61
	s_cmpk_eq_i32 s60, 0x1f00
	s_cselect_b32 s65, s19, s63
	s_cselect_b32 s64, s21, s62
	s_cselect_b32 s63, s53, s94
	s_cselect_b32 s62, s57, s93
	v_lshl_add_u64 v[4:5], v[94:95], 0, s[60:61]
	s_add_i32 m0, s24, 0xc000
	ds_read_b128 v[186:189], v244
	ds_read_b128 v[190:193], v244 offset:1024
	ds_read_b128 v[196:199], v244 offset:2048
	ds_read_b128 v[200:203], v244 offset:3072
	ds_read_b128 v[204:207], v244 offset:4096
	ds_read_b128 v[208:211], v244 offset:5120
	ds_read_b128 v[212:215], v244 offset:6144
	ds_read_b128 v[246:249], v244 offset:7168
	global_load_lds_dwordx4 v[4:5], off
	v_lshl_add_u64 v[4:5], v[96:97], 0, s[60:61]
	s_add_i32 m0, s24, 0xe000
	s_nop 0
	global_load_lds_dwordx4 v[4:5], off
	s_waitcnt vmcnt(8)
	s_waitcnt lgkmcnt(0)
	s_barrier
	s_setprio 1
	s_waitcnt lgkmcnt(0)
	v_mfma_f32_16x16x32_bf16 v[146:149], v[98:101], v[186:189], v[146:149]
	v_mfma_f32_16x16x32_bf16 v[146:149], v[102:105], v[190:193], v[146:149]
	v_mfma_f32_16x16x32_bf16 v[138:141], v[98:101], v[196:199], v[138:141]
	v_mfma_f32_16x16x32_bf16 v[138:141], v[102:105], v[200:203], v[138:141]
	v_mfma_f32_16x16x32_bf16 v[130:133], v[98:101], v[204:207], v[130:133]
	v_mfma_f32_16x16x32_bf16 v[130:133], v[102:105], v[208:211], v[130:133]
	v_mfma_f32_16x16x32_bf16 v[122:125], v[98:101], v[212:215], v[122:125]
	v_mfma_f32_16x16x32_bf16 v[122:125], v[102:105], v[246:249], v[122:125]
	v_mfma_f32_16x16x32_bf16 v[118:121], v[106:109], v[212:215], v[118:121]
	v_mfma_f32_16x16x32_bf16 v[118:121], v[166:169], v[246:249], v[118:121]
	v_mfma_f32_16x16x32_bf16 v[126:129], v[106:109], v[204:207], v[126:129]
	v_mfma_f32_16x16x32_bf16 v[126:129], v[166:169], v[208:211], v[126:129]
	v_mfma_f32_16x16x32_bf16 v[134:137], v[106:109], v[196:199], v[134:137]
	v_mfma_f32_16x16x32_bf16 v[134:137], v[166:169], v[200:203], v[134:137]
	v_mfma_f32_16x16x32_bf16 v[142:145], v[106:109], v[186:189], v[142:145]
	v_mfma_f32_16x16x32_bf16 v[142:145], v[166:169], v[190:193], v[142:145]
	s_setprio 0
	s_setprio 1
	v_mfma_f32_16x16x32_bf16 v[66:69], v[170:173], v[186:189], v[66:69]
	v_mfma_f32_16x16x32_bf16 v[66:69], v[174:177], v[190:193], v[66:69]
	v_mfma_f32_16x16x32_bf16 v[58:61], v[170:173], v[196:199], v[58:61]
	v_mfma_f32_16x16x32_bf16 v[58:61], v[174:177], v[200:203], v[58:61]
	v_mfma_f32_16x16x32_bf16 v[50:53], v[170:173], v[204:207], v[50:53]
	v_mfma_f32_16x16x32_bf16 v[50:53], v[174:177], v[208:211], v[50:53]
	v_mfma_f32_16x16x32_bf16 v[42:45], v[170:173], v[212:215], v[42:45]
	v_mfma_f32_16x16x32_bf16 v[42:45], v[174:177], v[246:249], v[42:45]
	v_mfma_f32_16x16x32_bf16 v[38:41], v[178:181], v[212:215], v[38:41]
	v_mfma_f32_16x16x32_bf16 v[38:41], v[182:185], v[246:249], v[38:41]
	v_mfma_f32_16x16x32_bf16 v[46:49], v[178:181], v[204:207], v[46:49]
	v_mfma_f32_16x16x32_bf16 v[46:49], v[182:185], v[208:211], v[46:49]
	v_mfma_f32_16x16x32_bf16 v[54:57], v[178:181], v[196:199], v[54:57]
	v_mfma_f32_16x16x32_bf16 v[54:57], v[182:185], v[200:203], v[54:57]
	v_mfma_f32_16x16x32_bf16 v[62:65], v[178:181], v[186:189], v[62:65]
	v_mfma_f32_16x16x32_bf16 v[62:65], v[182:185], v[190:193], v[62:65]
	s_setprio 0
	s_barrier
	s_add_i32 s93, s83, s2
	v_lshl_add_u64 v[216:217], s[62:63], 0, v[152:153]
	s_mov_b32 m0, s93
	ds_read_b128 v[186:189], v244 offset:16384
	ds_read_b128 v[190:193], v244 offset:17408
	ds_read_b128 v[196:199], v244 offset:18432
	ds_read_b128 v[200:203], v244 offset:19456
	ds_read_b128 v[204:207], v244 offset:20480
	ds_read_b128 v[208:211], v244 offset:21504
	ds_read_b128 v[212:215], v244 offset:22528
	ds_read_b128 v[246:249], v244 offset:23552
	global_load_lds_dwordx4 v[216:217], off
	s_add_i32 m0, s93, 0x2000
	s_add_u32 s94, s62, 0x100000
	v_lshl_add_u64 v[250:251], s[62:63], 0, v[156:157]
	s_addc_u32 s95, s63, 0
	s_add_i32 s93, s86, s2
	global_load_lds_dwordx4 v[250:251], off
	v_lshl_add_u64 v[4:5], s[94:95], 0, v[152:153]
	s_mov_b32 m0, s93
	v_lshl_add_u64 v[252:253], s[64:65], 0, v[150:151]
	global_load_lds_dwordx4 v[4:5], off
	v_lshl_add_u64 v[4:5], s[94:95], 0, v[156:157]
	s_add_i32 m0, s93, 0x2000
	v_lshl_add_u64 v[222:223], s[64:65], 0, v[154:155]
	global_load_lds_dwordx4 v[4:5], off
	s_mov_b32 m0, s24
	s_nop 0
	global_load_lds_dwordx4 v[252:253], off
	s_mov_b32 m0, s25
	s_nop 0
	global_load_lds_dwordx4 v[222:223], off
	s_waitcnt vmcnt(8)
	s_waitcnt lgkmcnt(0)
	s_barrier
; #define PG8_STAGE(bufoff, gbase, voff) do { _Pragma("unroll") for (int _i = 0; _i < 2; ++_i) \
;         __builtin_amdgcn_global_load_lds((const unsigned*)((const char*)(gbase) + (voff)[_i]), (PG8_LAS unsigned*)(lds + (bufoff) + ldsw + _i * 8192), 16, 0, 0); } while (0)
; #define PG8_LDA(dst, b, h) do { _Pragma("unroll") for (int m = 0; m < 4; ++m) _Pragma("unroll") for (int k = 0; k < 2; ++k) dst[m][k] = *(const PG8_LAS bf16x8*)(lds + PG8_SA(b, h) + aoff + m * 2048 + k * 1024); } while (0)
; #define PG8_LDB(dst, b, h) do { _Pragma("unroll") for (int n = 0; n < 2; ++n) _Pragma("unroll") for (int k = 0; k < 2; ++k) dst[n][k] = *(const PG8_LAS bf16x8*)(lds + PG8_SB(b, h) + boff + n * 2048 + k * 1024); } while (0)
; #define PG8_MMA(ai, bj, At, Bt) do { __builtin_amdgcn_s_setprio(1); _Pragma("unroll") for (int m = 0; m < 4; ++m) _Pragma("unroll") for (int n = 0; n < 2; ++n) _Pragma("unroll") for (int k = 0; k < 2; ++k) \
;         acc[ai][bj][m][n] = __builtin_amdgcn_mfma_f32_16x16x32_bf16(Bt[n][k], At[m][k], acc[ai][bj][m][n], 0, 0, 0); __builtin_amdgcn_s_setprio(0); } while (0)
; #define PG8_WAIT_V(n) asm volatile("s_waitcnt vmcnt(" #n ")" ::: "memory")
; #define PG8_WAIT_L(n) asm volatile("s_waitcnt lgkmcnt(" #n ")" ::: "memory")
; #define PG8_BAR __builtin_amdgcn_s_barrier()
; #define PG8_SCHED __builtin_amdgcn_sched_barrier(0)
; template <class Epi, class Sched, bool ALIGN_EPI = false, bool SP2 = false>
; __device__ __forceinline__ void gemm_phase(PG8_LAS unsigned char* lds, const Gemm g, const Sched& S, const Epi& E) {
;     ...
;             PG8_LDA(At, 0, 1); PG8_STAGE(PG8_SB(0, 0), b2, voffB); PG8_STAGE(PG8_SB(0, 1), b2 + hstep, voffB); PG8_STAGE(PG8_SA(0, 0), a2, voffA);
;             PG8_WAIT_V(8); PG8_WAIT_L(0); PG8_BAR; PG8_MMA(1, 0, At, B0); PG8_MMA(1, 1, At, B1); PG8_BAR; PG8_SCHED;
;             PG8_LDB(B0, 1, 0); PG8_LDB(B1, 1, 1); PG8_SCHED; PG8_LDA(At, 1, 0); PG8_STAGE(PG8_SA(0, 1), a2 + hstep, voffA);
;             PG8_WAIT_V(8); PG8_WAIT_L(0); PG8_BAR; PG8_MMA(0, 0, At, B0); PG8_MMA(0, 1, At, B1); PG8_BAR; PG8_SCHED;
	s_setprio 1
	s_waitcnt lgkmcnt(0)
	v_mfma_f32_16x16x32_bf16 v[114:117], v[98:101], v[186:189], v[114:117]
	v_mfma_f32_16x16x32_bf16 v[114:117], v[102:105], v[190:193], v[114:117]
	v_mfma_f32_16x16x32_bf16 v[90:93], v[98:101], v[196:199], v[90:93]
	v_mfma_f32_16x16x32_bf16 v[90:93], v[102:105], v[200:203], v[90:93]
	v_mfma_f32_16x16x32_bf16 v[82:85], v[98:101], v[204:207], v[82:85]
	v_mfma_f32_16x16x32_bf16 v[82:85], v[102:105], v[208:211], v[82:85]
	v_mfma_f32_16x16x32_bf16 v[74:77], v[98:101], v[212:215], v[74:77]
	v_mfma_f32_16x16x32_bf16 v[74:77], v[102:105], v[246:249], v[74:77]
	v_mfma_f32_16x16x32_bf16 v[70:73], v[106:109], v[212:215], v[70:73]
	v_mfma_f32_16x16x32_bf16 v[70:73], v[166:169], v[246:249], v[70:73]
	v_mfma_f32_16x16x32_bf16 v[78:81], v[106:109], v[204:207], v[78:81]
	v_mfma_f32_16x16x32_bf16 v[78:81], v[166:169], v[208:211], v[78:81]
	v_mfma_f32_16x16x32_bf16 v[86:89], v[106:109], v[196:199], v[86:89]
	v_mfma_f32_16x16x32_bf16 v[86:89], v[166:169], v[200:203], v[86:89]
	v_mfma_f32_16x16x32_bf16 v[110:113], v[106:109], v[186:189], v[110:113]
	v_mfma_f32_16x16x32_bf16 v[110:113], v[166:169], v[190:193], v[110:113]
	s_setprio 0
	s_setprio 1
	v_mfma_f32_16x16x32_bf16 v[34:37], v[170:173], v[186:189], v[34:37]
	v_mfma_f32_16x16x32_bf16 v[34:37], v[174:177], v[190:193], v[34:37]
	v_mfma_f32_16x16x32_bf16 v[26:29], v[170:173], v[196:199], v[26:29]
	v_mfma_f32_16x16x32_bf16 v[26:29], v[174:177], v[200:203], v[26:29]
	v_mfma_f32_16x16x32_bf16 v[18:21], v[170:173], v[204:207], v[18:21]
	v_mfma_f32_16x16x32_bf16 v[18:21], v[174:177], v[208:211], v[18:21]
	v_mfma_f32_16x16x32_bf16 v[10:13], v[170:173], v[212:215], v[10:13]
	v_mfma_f32_16x16x32_bf16 v[10:13], v[174:177], v[246:249], v[10:13]
	v_mfma_f32_16x16x32_bf16 v[4:7], v[178:181], v[212:215], v[6:9]
	v_mfma_f32_16x16x32_bf16 v[4:7], v[182:185], v[246:249], v[4:7]
	v_mfma_f32_16x16x32_bf16 v[14:17], v[178:181], v[204:207], v[14:17]
	v_mfma_f32_16x16x32_bf16 v[14:17], v[182:185], v[208:211], v[14:17]
	v_mfma_f32_16x16x32_bf16 v[22:25], v[178:181], v[196:199], v[22:25]
	v_mfma_f32_16x16x32_bf16 v[22:25], v[182:185], v[200:203], v[22:25]
	v_mfma_f32_16x16x32_bf16 v[30:33], v[178:181], v[186:189], v[30:33]
	v_mfma_f32_16x16x32_bf16 v[30:33], v[182:185], v[190:193], v[30:33]
	s_setprio 0
	s_barrier
	s_add_i32 s93, 0, 0x18000
	v_add_u32_e32 v3, s93, v219
	s_add_i32 s94, 0, 0x1c000
	ds_read_b128 v[98:101], v3
	ds_read_b128 v[102:105], v3 offset:1024
	ds_read_b128 v[106:109], v3 offset:2048
	ds_read_b128 v[166:169], v3 offset:3072
	v_add_u32_e32 v3, s94, v219
	ds_read_b128 v[170:173], v3
	ds_read_b128 v[174:177], v3 offset:1024
	ds_read_b128 v[178:181], v3 offset:2048
	ds_read_b128 v[182:185], v3 offset:3072
	s_add_u32 s64, s64, 0x100000
	s_addc_u32 s65, s65, 0
	s_mov_b32 m0, s26
	v_lshl_add_u64 v[8:9], s[64:65], 0, v[150:151]
	ds_read_b128 v[186:189], v244 offset:32768
	ds_read_b128 v[190:193], v244 offset:33792
	ds_read_b128 v[196:199], v244 offset:34816
	ds_read_b128 v[200:203], v244 offset:35840
	ds_read_b128 v[204:207], v244 offset:36864
	ds_read_b128 v[208:211], v244 offset:37888
	ds_read_b128 v[212:215], v244 offset:38912
	ds_read_b128 v[246:249], v244 offset:39936
	global_load_lds_dwordx4 v[8:9], off
	v_lshl_add_u64 v[8:9], s[64:65], 0, v[154:155]
	s_mov_b32 m0, s27
	s_nop 0
	global_load_lds_dwordx4 v[8:9], off
	s_waitcnt vmcnt(8)
	s_waitcnt lgkmcnt(0)
	s_barrier
	s_setprio 1
	s_waitcnt lgkmcnt(0)
	v_mfma_f32_16x16x32_bf16 v[146:149], v[98:101], v[186:189], v[146:149]
	v_mfma_f32_16x16x32_bf16 v[146:149], v[102:105], v[190:193], v[146:149]
	v_mfma_f32_16x16x32_bf16 v[138:141], v[98:101], v[196:199], v[138:141]
	v_mfma_f32_16x16x32_bf16 v[138:141], v[102:105], v[200:203], v[138:141]
	v_mfma_f32_16x16x32_bf16 v[130:133], v[98:101], v[204:207], v[130:133]
	v_mfma_f32_16x16x32_bf16 v[130:133], v[102:105], v[208:211], v[130:133]
	v_mfma_f32_16x16x32_bf16 v[122:125], v[98:101], v[212:215], v[122:125]
	v_mfma_f32_16x16x32_bf16 v[122:125], v[102:105], v[246:249], v[122:125]
	v_mfma_f32_16x16x32_bf16 v[118:121], v[106:109], v[212:215], v[118:121]
	v_mfma_f32_16x16x32_bf16 v[118:121], v[166:169], v[246:249], v[118:121]
	v_mfma_f32_16x16x32_bf16 v[126:129], v[106:109], v[204:207], v[126:129]
	v_mfma_f32_16x16x32_bf16 v[126:129], v[166:169], v[208:211], v[126:129]
	v_mfma_f32_16x16x32_bf16 v[134:137], v[106:109], v[196:199], v[134:137]
	v_mfma_f32_16x16x32_bf16 v[134:137], v[166:169], v[200:203], v[134:137]
	v_mfma_f32_16x16x32_bf16 v[142:145], v[106:109], v[186:189], v[142:145]
	v_mfma_f32_16x16x32_bf16 v[142:145], v[166:169], v[190:193], v[142:145]
	s_setprio 0
	s_setprio 1
	v_mfma_f32_16x16x32_bf16 v[66:69], v[170:173], v[186:189], v[66:69]
	v_mfma_f32_16x16x32_bf16 v[66:69], v[174:177], v[190:193], v[66:69]
	v_mfma_f32_16x16x32_bf16 v[58:61], v[170:173], v[196:199], v[58:61]
	v_mfma_f32_16x16x32_bf16 v[58:61], v[174:177], v[200:203], v[58:61]
	v_mfma_f32_16x16x32_bf16 v[50:53], v[170:173], v[204:207], v[50:53]
	v_mfma_f32_16x16x32_bf16 v[50:53], v[174:177], v[208:211], v[50:53]
	v_mfma_f32_16x16x32_bf16 v[42:45], v[170:173], v[212:215], v[42:45]
	v_mfma_f32_16x16x32_bf16 v[42:45], v[174:177], v[246:249], v[42:45]
	v_mfma_f32_16x16x32_bf16 v[38:41], v[178:181], v[212:215], v[38:41]
	v_mfma_f32_16x16x32_bf16 v[38:41], v[182:185], v[246:249], v[38:41]
	v_mfma_f32_16x16x32_bf16 v[46:49], v[178:181], v[204:207], v[46:49]
	v_mfma_f32_16x16x32_bf16 v[46:49], v[182:185], v[208:211], v[46:49]
	v_mfma_f32_16x16x32_bf16 v[54:57], v[178:181], v[196:199], v[54:57]
	v_mfma_f32_16x16x32_bf16 v[54:57], v[182:185], v[200:203], v[54:57]
	v_mfma_f32_16x16x32_bf16 v[62:65], v[178:181], v[186:189], v[62:65]
	v_mfma_f32_16x16x32_bf16 v[62:65], v[182:185], v[190:193], v[62:65]
	s_setprio 0
	s_barrier
; #define PG8_STAGE(bufoff, gbase, voff) do { _Pragma("unroll") for (int _i = 0; _i < 2; ++_i) \
;         __builtin_amdgcn_global_load_lds((const unsigned*)((const char*)(gbase) + (voff)[_i]), (PG8_LAS unsigned*)(lds + (bufoff) + ldsw + _i * 8192), 16, 0, 0); } while (0)
; #define PG8_LDA(dst, b, h) do { _Pragma("unroll") for (int m = 0; m < 4; ++m) _Pragma("unroll") for (int k = 0; k < 2; ++k) dst[m][k] = *(const PG8_LAS bf16x8*)(lds + PG8_SA(b, h) + aoff + m * 2048 + k * 1024); } while (0)
; #define PG8_MMA(ai, bj, At, Bt) do { __builtin_amdgcn_s_setprio(1); _Pragma("unroll") for (int m = 0; m < 4; ++m) _Pragma("unroll") for (int n = 0; n < 2; ++n) _Pragma("unroll") for (int k = 0; k < 2; ++k) \
;         acc[ai][bj][m][n] = __builtin_amdgcn_mfma_f32_16x16x32_bf16(Bt[n][k], At[m][k], acc[ai][bj][m][n], 0, 0, 0); __builtin_amdgcn_s_setprio(0); } while (0)
; #define PG8_WAIT_V(n) asm volatile("s_waitcnt vmcnt(" #n ")" ::: "memory")
; #define PG8_WAIT_L(n) asm volatile("s_waitcnt lgkmcnt(" #n ")" ::: "memory")
; #define PG8_BAR __builtin_amdgcn_s_barrier()
; #define PG8_SCHED __builtin_amdgcn_sched_barrier(0)
; template <class Epi, class Sched, bool ALIGN_EPI = false, bool SP2 = false>
; __device__ __forceinline__ void gemm_phase(PG8_LAS unsigned char* lds, const Gemm g, const Sched& S, const Epi& E) {
;     ...
;             PG8_LDA(At, 1, 1); PG8_STAGE(PG8_SB(1, 0), b3, voffB); PG8_STAGE(PG8_SB(1, 1), b3 + hstep, voffB); PG8_STAGE(PG8_SA(1, 0), a3, voffA);
;             PG8_WAIT_V(8); PG8_WAIT_L(0); PG8_BAR; PG8_MMA(1, 0, At, B0); PG8_MMA(1, 1, At, B1); PG8_BAR; PG8_SCHED;
	s_add_i32 s64, s93, s2
	v_lshl_add_u64 v[8:9], v[216:217], 0, s[14:15]
	s_mov_b32 m0, s64
	ds_read_b128 v[186:189], v244 offset:49152
	ds_read_b128 v[190:193], v244 offset:50176
	ds_read_b128 v[196:199], v244 offset:51200
	ds_read_b128 v[200:203], v244 offset:52224
	ds_read_b128 v[204:207], v244 offset:53248
	ds_read_b128 v[208:211], v244 offset:54272
	ds_read_b128 v[212:215], v244 offset:55296
	ds_read_b128 v[246:249], v244 offset:56320
	global_load_lds_dwordx4 v[8:9], off
	s_add_i32 m0, s64, 0x2000
	s_add_u32 s62, s62, 0x100080
	v_lshl_add_u64 v[8:9], v[250:251], 0, s[14:15]
	s_addc_u32 s63, s63, 0
	s_add_i32 s64, s94, s2
	global_load_lds_dwordx4 v[8:9], off
	v_lshl_add_u64 v[8:9], s[62:63], 0, v[152:153]
	s_mov_b32 m0, s64
	s_nop 0
	global_load_lds_dwordx4 v[8:9], off
	v_lshl_add_u64 v[8:9], s[62:63], 0, v[156:157]
	s_add_i32 m0, s64, 0x2000
	s_nop 0
	global_load_lds_dwordx4 v[8:9], off
	v_lshl_add_u64 v[8:9], v[252:253], 0, s[14:15]
	s_mov_b32 m0, s66
	s_nop 0
	global_load_lds_dwordx4 v[8:9], off
	v_lshl_add_u64 v[8:9], v[222:223], 0, s[14:15]
	s_mov_b32 m0, s67
	s_nop 0
	global_load_lds_dwordx4 v[8:9], off
	s_waitcnt vmcnt(8)
	s_waitcnt lgkmcnt(0)
	s_barrier
	s_setprio 1
	s_waitcnt lgkmcnt(0)
	v_mfma_f32_16x16x32_bf16 v[114:117], v[98:101], v[186:189], v[114:117]
	v_mfma_f32_16x16x32_bf16 v[114:117], v[102:105], v[190:193], v[114:117]
	v_mfma_f32_16x16x32_bf16 v[90:93], v[98:101], v[196:199], v[90:93]
	v_mfma_f32_16x16x32_bf16 v[90:93], v[102:105], v[200:203], v[90:93]
	v_mfma_f32_16x16x32_bf16 v[82:85], v[98:101], v[204:207], v[82:85]
	v_mfma_f32_16x16x32_bf16 v[82:85], v[102:105], v[208:211], v[82:85]
	v_mfma_f32_16x16x32_bf16 v[74:77], v[98:101], v[212:215], v[74:77]
	v_mfma_f32_16x16x32_bf16 v[74:77], v[102:105], v[246:249], v[74:77]
	v_mfma_f32_16x16x32_bf16 v[70:73], v[106:109], v[212:215], v[70:73]
	v_mfma_f32_16x16x32_bf16 v[70:73], v[166:169], v[246:249], v[70:73]
	v_mfma_f32_16x16x32_bf16 v[78:81], v[106:109], v[204:207], v[78:81]
	v_mfma_f32_16x16x32_bf16 v[78:81], v[166:169], v[208:211], v[78:81]
	v_mfma_f32_16x16x32_bf16 v[86:89], v[106:109], v[196:199], v[86:89]
	v_mfma_f32_16x16x32_bf16 v[86:89], v[166:169], v[200:203], v[86:89]
	v_mfma_f32_16x16x32_bf16 v[110:113], v[106:109], v[186:189], v[110:113]
	v_mfma_f32_16x16x32_bf16 v[110:113], v[166:169], v[190:193], v[110:113]
	s_setprio 0
	s_setprio 1
	v_mfma_f32_16x16x32_bf16 v[34:37], v[170:173], v[186:189], v[34:37]
	v_mfma_f32_16x16x32_bf16 v[34:37], v[174:177], v[190:193], v[34:37]
	v_mfma_f32_16x16x32_bf16 v[26:29], v[170:173], v[196:199], v[26:29]
	v_mfma_f32_16x16x32_bf16 v[26:29], v[174:177], v[200:203], v[26:29]
	v_mfma_f32_16x16x32_bf16 v[18:21], v[170:173], v[204:207], v[18:21]
	v_mfma_f32_16x16x32_bf16 v[18:21], v[174:177], v[208:211], v[18:21]
	v_mfma_f32_16x16x32_bf16 v[8:11], v[170:173], v[212:215], v[10:13]
	v_mfma_f32_16x16x32_bf16 v[10:13], v[174:177], v[246:249], v[8:11]
	v_mfma_f32_16x16x32_bf16 v[4:7], v[178:181], v[212:215], v[4:7]
	v_mfma_f32_16x16x32_bf16 v[6:9], v[182:185], v[246:249], v[4:7]
	v_mfma_f32_16x16x32_bf16 v[14:17], v[178:181], v[204:207], v[14:17]
	v_mfma_f32_16x16x32_bf16 v[14:17], v[182:185], v[208:211], v[14:17]
	v_mfma_f32_16x16x32_bf16 v[22:25], v[178:181], v[196:199], v[22:25]
	v_mfma_f32_16x16x32_bf16 v[22:25], v[182:185], v[200:203], v[22:25]
	v_mfma_f32_16x16x32_bf16 v[30:33], v[178:181], v[186:189], v[30:33]
	v_mfma_f32_16x16x32_bf16 v[30:33], v[182:185], v[190:193], v[30:33]
	s_setprio 0
	s_barrier
	s_add_i32 s92, s92, 2
	s_add_u32 s60, s60, 0x100
	s_addc_u32 s61, s61, 0
	s_cmp_gt_u32 s92, 61
	s_cbranch_scc1 .LBB0_914

; #define PG8_STAGE(bufoff, gbase, voff) do { _Pragma("unroll") for (int _i = 0; _i < 2; ++_i) \
;         __builtin_amdgcn_global_load_lds((const unsigned*)((const char*)(gbase) + (voff)[_i]), (PG8_LAS unsigned*)(lds + (bufoff) + ldsw + _i * 8192), 16, 0, 0); } while (0)
; #define PG8_LDA(dst, b, h) do { _Pragma("unroll") for (int m = 0; m < 4; ++m) _Pragma("unroll") for (int k = 0; k < 2; ++k) dst[m][k] = *(const PG8_LAS bf16x8*)(lds + PG8_SA(b, h) + aoff + m * 2048 + k * 1024); } while (0)
; #define PG8_LDB(dst, b, h) do { _Pragma("unroll") for (int n = 0; n < 2; ++n) _Pragma("unroll") for (int k = 0; k < 2; ++k) dst[n][k] = *(const PG8_LAS bf16x8*)(lds + PG8_SB(b, h) + boff + n * 2048 + k * 1024); } while (0)
; #define PG8_MMA(ai, bj, At, Bt) do { __builtin_amdgcn_s_setprio(1); _Pragma("unroll") for (int m = 0; m < 4; ++m) _Pragma("unroll") for (int n = 0; n < 2; ++n) _Pragma("unroll") for (int k = 0; k < 2; ++k) \
;         acc[ai][bj][m][n] = __builtin_amdgcn_mfma_f32_16x16x32_bf16(Bt[n][k], At[m][k], acc[ai][bj][m][n], 0, 0, 0); __builtin_amdgcn_s_setprio(0); } while (0)
; #define PG8_BAR __builtin_amdgcn_s_barrier()
; template <class Epi, class Sched, bool ALIGN_EPI = false, bool SP2 = false>
; __device__ __forceinline__ void gemm_phase(PG8_LAS unsigned char* lds, const Gemm g, const Sched& S, const Epi& E) {
;     ...
;             const bool last = (t == nt - 2);
;             const char* a1 = cA + (size_t)(t + 1) * kstep;
;             const char* a2 = last ? nA : cA + (size_t)(t + 2) * kstep; const char* b2 = last ? nB : cB + (size_t)(t + 2) * kstep;
;             const char* a3 = a2 + kstep; const char* b3 = b2 + kstep;
;             if (last && has_next) S.a_ready(nxt);
;             if constexpr (Epi::MIDK) { if (t == (nt >> 1)) { E.midk(acc, wr, fr); asm volatile("s_waitcnt lgkmcnt(0)" ::: "memory"); } }
;             if constexpr (SP2) {
;             PG8_LDB(B0, 0, 0); PG8_LDB(B1, 0, 1); PG8_SCHED; PG8_LDA(At, 0, 0); PG8_STAGE(PG8_SA(1, 1), a1 + hstep, voffA);
;             PG8_WAIT_V(8); PG8_WAIT_L(0); PG8_BAR; PG8_MMA(0, 0, At, B0); PG8_MMA(0, 1, At, B1); PG8_BAR; PG8_SCHED;
;             PG8_LDA(At, 0, 1); PG8_STAGE(PG8_SB(0, 0), b2, voffB); PG8_STAGE(PG8_SB(0, 1), b2 + hstep, voffB); PG8_STAGE(PG8_SA(0, 0), a2, voffA);
;             PG8_WAIT_V(8); PG8_WAIT_L(0); PG8_BAR; PG8_MMA(1, 0, At, B0); PG8_MMA(1, 1, At, B1); PG8_BAR; PG8_SCHED;
.LBB0_1251:
	ds_read_b128 v[130:133], v177
	ds_read_b128 v[134:137], v177 offset:1024
	ds_read_b128 v[138:141], v177 offset:2048
	ds_read_b128 v[142:145], v177 offset:3072
	ds_read_b128 v[162:165], v178
	ds_read_b128 v[180:183], v178 offset:1024
	ds_read_b128 v[184:187], v178 offset:2048
	ds_read_b128 v[188:191], v178 offset:3072
	s_add_u32 s40, s36, 0xfff00080
	s_addc_u32 s41, s37, -1
	s_cmp_eq_u32 s58, 60
	s_cselect_b32 s43, s15, s41
	s_cselect_b32 s42, s17, s40
	s_cselect_b32 s41, s54, s57
	s_cselect_b32 s40, s55, s56
	ds_read_b128 v[196:199], v179
	ds_read_b128 v[200:203], v179 offset:1024
	ds_read_b128 v[204:207], v179 offset:2048
	ds_read_b128 v[208:211], v179 offset:3072
	ds_read_b128 v[212:215], v179 offset:4096
	ds_read_b128 v[220:223], v179 offset:5120
	ds_read_b128 v[224:227], v179 offset:6144
	ds_read_b128 v[228:231], v179 offset:7168
	s_add_i32 m0, s24, 0xc000
	s_nop 0
	global_load_lds_dwordx4 v146, s[36:37]
	s_add_i32 m0, s24, 0xe000
	s_nop 0
	global_load_lds_dwordx4 v150, s[36:37]
	s_waitcnt lgkmcnt(0)
	s_setprio 1
	v_mfma_f32_16x16x32_bf16 v[126:129], v[130:133], v[196:199], v[126:129]
	v_mfma_f32_16x16x32_bf16 v[126:129], v[134:137], v[200:203], v[126:129]
	v_mfma_f32_16x16x32_bf16 v[110:113], v[130:133], v[204:207], v[110:113]
	v_mfma_f32_16x16x32_bf16 v[110:113], v[134:137], v[208:211], v[110:113]
	v_mfma_f32_16x16x32_bf16 v[94:97], v[130:133], v[212:215], v[94:97]
	v_mfma_f32_16x16x32_bf16 v[94:97], v[134:137], v[220:223], v[94:97]
	v_mfma_f32_16x16x32_bf16 v[78:81], v[130:133], v[224:227], v[78:81]
	v_mfma_f32_16x16x32_bf16 v[78:81], v[134:137], v[228:231], v[78:81]
	v_mfma_f32_16x16x32_bf16 v[74:77], v[138:141], v[224:227], v[74:77]
	v_mfma_f32_16x16x32_bf16 v[74:77], v[142:145], v[228:231], v[74:77]
	v_mfma_f32_16x16x32_bf16 v[90:93], v[138:141], v[212:215], v[90:93]
	v_mfma_f32_16x16x32_bf16 v[90:93], v[142:145], v[220:223], v[90:93]
	v_mfma_f32_16x16x32_bf16 v[106:109], v[138:141], v[204:207], v[106:109]
	v_mfma_f32_16x16x32_bf16 v[106:109], v[142:145], v[208:211], v[106:109]
	v_mfma_f32_16x16x32_bf16 v[122:125], v[138:141], v[196:199], v[122:125]
	v_mfma_f32_16x16x32_bf16 v[122:125], v[142:145], v[200:203], v[122:125]
	v_mfma_f32_16x16x32_bf16 v[118:121], v[162:165], v[196:199], v[118:121]
	v_mfma_f32_16x16x32_bf16 v[118:121], v[180:183], v[200:203], v[118:121]
	v_mfma_f32_16x16x32_bf16 v[102:105], v[162:165], v[204:207], v[102:105]
	v_mfma_f32_16x16x32_bf16 v[102:105], v[180:183], v[208:211], v[102:105]
	v_mfma_f32_16x16x32_bf16 v[86:89], v[162:165], v[212:215], v[86:89]
	v_mfma_f32_16x16x32_bf16 v[86:89], v[180:183], v[220:223], v[86:89]
	v_mfma_f32_16x16x32_bf16 v[70:73], v[162:165], v[224:227], v[70:73]
	v_mfma_f32_16x16x32_bf16 v[70:73], v[180:183], v[228:231], v[70:73]
	v_mfma_f32_16x16x32_bf16 v[66:69], v[184:187], v[224:227], v[66:69]
	v_mfma_f32_16x16x32_bf16 v[66:69], v[188:191], v[228:231], v[66:69]
	v_mfma_f32_16x16x32_bf16 v[82:85], v[184:187], v[212:215], v[82:85]
	v_mfma_f32_16x16x32_bf16 v[82:85], v[188:191], v[220:223], v[82:85]
	v_mfma_f32_16x16x32_bf16 v[98:101], v[184:187], v[204:207], v[98:101]
	v_mfma_f32_16x16x32_bf16 v[98:101], v[188:191], v[208:211], v[98:101]
	v_mfma_f32_16x16x32_bf16 v[114:117], v[184:187], v[196:199], v[114:117]
	v_mfma_f32_16x16x32_bf16 v[114:117], v[188:191], v[200:203], v[114:117]
	s_setprio 0
	s_waitcnt vmcnt(8)
	s_barrier
	ds_read_b128 v[196:199], v179 offset:16384
	ds_read_b128 v[200:203], v179 offset:17408
	ds_read_b128 v[204:207], v179 offset:18432
	ds_read_b128 v[208:211], v179 offset:19456
	ds_read_b128 v[212:215], v179 offset:20480
	ds_read_b128 v[220:223], v179 offset:21504
	ds_read_b128 v[224:227], v179 offset:22528
	ds_read_b128 v[228:231], v179 offset:23552
	s_add_u32 vcc_lo, s40, 0x100000
	s_addc_u32 vcc_hi, s41, 0
	s_add_i32 m0, s24, 0x10000
	s_nop 0
	global_load_lds_dwordx4 v148, s[40:41]
	s_add_i32 m0, s24, 0x12000
	s_nop 0
	global_load_lds_dwordx4 v152, s[40:41]
	s_add_i32 m0, s24, 0x14000
	s_nop 0
	global_load_lds_dwordx4 v148, vcc
	s_add_i32 m0, s24, 0x16000
	s_nop 0
	global_load_lds_dwordx4 v152, vcc
	s_mov_b32 m0, s24
	s_nop 0
	global_load_lds_dwordx4 v146, s[42:43]
	s_add_i32 m0, s24, 0x2000
	s_nop 0
	global_load_lds_dwordx4 v150, s[42:43]
	s_waitcnt lgkmcnt(0)
	s_setprio 1
	v_mfma_f32_16x16x32_bf16 v[62:65], v[130:133], v[196:199], v[62:65]
	v_mfma_f32_16x16x32_bf16 v[62:65], v[134:137], v[200:203], v[62:65]
	v_mfma_f32_16x16x32_bf16 v[46:49], v[130:133], v[204:207], v[46:49]
	v_mfma_f32_16x16x32_bf16 v[46:49], v[134:137], v[208:211], v[46:49]
	v_mfma_f32_16x16x32_bf16 v[30:33], v[130:133], v[212:215], v[30:33]
	v_mfma_f32_16x16x32_bf16 v[30:33], v[134:137], v[220:223], v[30:33]
	v_mfma_f32_16x16x32_bf16 v[14:17], v[130:133], v[224:227], v[14:17]
	v_mfma_f32_16x16x32_bf16 v[14:17], v[134:137], v[228:231], v[14:17]
	v_mfma_f32_16x16x32_bf16 v[10:13], v[138:141], v[224:227], v[10:13]
	v_mfma_f32_16x16x32_bf16 v[10:13], v[142:145], v[228:231], v[10:13]
	v_mfma_f32_16x16x32_bf16 v[26:29], v[138:141], v[212:215], v[26:29]
	v_mfma_f32_16x16x32_bf16 v[26:29], v[142:145], v[220:223], v[26:29]
	v_mfma_f32_16x16x32_bf16 v[42:45], v[138:141], v[204:207], v[42:45]
	v_mfma_f32_16x16x32_bf16 v[42:45], v[142:145], v[208:211], v[42:45]
	v_mfma_f32_16x16x32_bf16 v[58:61], v[138:141], v[196:199], v[58:61]
	v_mfma_f32_16x16x32_bf16 v[58:61], v[142:145], v[200:203], v[58:61]
	v_mfma_f32_16x16x32_bf16 v[54:57], v[162:165], v[196:199], v[54:57]
	v_mfma_f32_16x16x32_bf16 v[54:57], v[180:183], v[200:203], v[54:57]
	v_mfma_f32_16x16x32_bf16 v[38:41], v[162:165], v[204:207], v[38:41]
	v_mfma_f32_16x16x32_bf16 v[38:41], v[180:183], v[208:211], v[38:41]
	v_mfma_f32_16x16x32_bf16 v[22:25], v[162:165], v[212:215], v[22:25]
	v_mfma_f32_16x16x32_bf16 v[22:25], v[180:183], v[220:223], v[22:25]
	v_mfma_f32_16x16x32_bf16 v[6:9], v[162:165], v[224:227], v[6:9]
	v_mfma_f32_16x16x32_bf16 v[6:9], v[180:183], v[228:231], v[6:9]
	v_mfma_f32_16x16x32_bf16 v[2:5], v[184:187], v[224:227], v[2:5]
	v_mfma_f32_16x16x32_bf16 v[2:5], v[188:191], v[228:231], v[2:5]
	v_mfma_f32_16x16x32_bf16 v[18:21], v[184:187], v[212:215], v[18:21]
	v_mfma_f32_16x16x32_bf16 v[18:21], v[188:191], v[220:223], v[18:21]
	v_mfma_f32_16x16x32_bf16 v[34:37], v[184:187], v[204:207], v[34:37]
	v_mfma_f32_16x16x32_bf16 v[34:37], v[188:191], v[208:211], v[34:37]
	v_mfma_f32_16x16x32_bf16 v[50:53], v[184:187], v[196:199], v[50:53]
	v_mfma_f32_16x16x32_bf16 v[50:53], v[188:191], v[200:203], v[50:53]
	s_setprio 0
	s_waitcnt vmcnt(8)
	s_barrier
; #define PG8_STAGE(bufoff, gbase, voff) do { _Pragma("unroll") for (int _i = 0; _i < 2; ++_i) \
;         __builtin_amdgcn_global_load_lds((const unsigned*)((const char*)(gbase) + (voff)[_i]), (PG8_LAS unsigned*)(lds + (bufoff) + ldsw + _i * 8192), 16, 0, 0); } while (0)
; #define PG8_LDA(dst, b, h) do { _Pragma("unroll") for (int m = 0; m < 4; ++m) _Pragma("unroll") for (int k = 0; k < 2; ++k) dst[m][k] = *(const PG8_LAS bf16x8*)(lds + PG8_SA(b, h) + aoff + m * 2048 + k * 1024); } while (0)
; #define PG8_LDB(dst, b, h) do { _Pragma("unroll") for (int n = 0; n < 2; ++n) _Pragma("unroll") for (int k = 0; k < 2; ++k) dst[n][k] = *(const PG8_LAS bf16x8*)(lds + PG8_SB(b, h) + boff + n * 2048 + k * 1024); } while (0)
; #define PG8_MMA(ai, bj, At, Bt) do { __builtin_amdgcn_s_setprio(1); _Pragma("unroll") for (int m = 0; m < 4; ++m) _Pragma("unroll") for (int n = 0; n < 2; ++n) _Pragma("unroll") for (int k = 0; k < 2; ++k) \
;         acc[ai][bj][m][n] = __builtin_amdgcn_mfma_f32_16x16x32_bf16(Bt[n][k], At[m][k], acc[ai][bj][m][n], 0, 0, 0); __builtin_amdgcn_s_setprio(0); } while (0)
; #define PG8_WAIT_V(n) asm volatile("s_waitcnt vmcnt(" #n ")" ::: "memory")
; #define PG8_WAIT_L(n) asm volatile("s_waitcnt lgkmcnt(" #n ")" ::: "memory")
; #define PG8_BAR __builtin_amdgcn_s_barrier()
; #define PG8_SCHED __builtin_amdgcn_sched_barrier(0)
; template <class Epi, class Sched, bool ALIGN_EPI = false, bool SP2 = false>
; __device__ __forceinline__ void gemm_phase(PG8_LAS unsigned char* lds, const Gemm g, const Sched& S, const Epi& E) {
;     ...
;             PG8_LDB(B0, 1, 0); PG8_LDB(B1, 1, 1); PG8_SCHED; PG8_LDA(At, 1, 0); PG8_STAGE(PG8_SA(0, 1), a2 + hstep, voffA);
;             PG8_WAIT_V(8); PG8_WAIT_L(0); PG8_BAR; PG8_MMA(0, 0, At, B0); PG8_MMA(0, 1, At, B1); PG8_BAR; PG8_SCHED;
;             PG8_LDA(At, 1, 1); PG8_STAGE(PG8_SB(1, 0), b3, voffB); PG8_STAGE(PG8_SB(1, 1), b3 + hstep, voffB); PG8_STAGE(PG8_SA(1, 0), a3, voffA);
;             PG8_WAIT_V(8); PG8_WAIT_L(0); PG8_BAR; PG8_MMA(1, 0, At, B0); PG8_MMA(1, 1, At, B1); PG8_BAR; PG8_SCHED;
	s_add_i32 s59, 0, 0x18000
	s_add_i32 s60, 0, 0x1c000
	v_add_u32_e32 v142, s59, v166
	v_add_u32_e32 v188, s60, v166
	ds_read_b128 v[130:133], v142
	ds_read_b128 v[134:137], v142 offset:1024
	ds_read_b128 v[138:141], v142 offset:2048
	ds_read_b128 v[142:145], v142 offset:3072
	ds_read_b128 v[162:165], v188
	ds_read_b128 v[180:183], v188 offset:1024
	ds_read_b128 v[184:187], v188 offset:2048
	ds_read_b128 v[188:191], v188 offset:3072
	ds_read_b128 v[196:199], v179 offset:32768
	ds_read_b128 v[200:203], v179 offset:33792
	ds_read_b128 v[204:207], v179 offset:34816
	ds_read_b128 v[208:211], v179 offset:35840
	ds_read_b128 v[212:215], v179 offset:36864
	ds_read_b128 v[220:223], v179 offset:37888
	ds_read_b128 v[224:227], v179 offset:38912
	ds_read_b128 v[228:231], v179 offset:39936
	s_add_u32 vcc_lo, s42, 0x100000
	s_addc_u32 vcc_hi, s43, 0
	s_add_i32 m0, s24, 0x4000
	s_nop 0
	global_load_lds_dwordx4 v146, vcc
	s_add_i32 m0, s24, 0x6000
	s_nop 0
	global_load_lds_dwordx4 v150, vcc
	s_waitcnt lgkmcnt(0)
	s_setprio 1
	v_mfma_f32_16x16x32_bf16 v[126:129], v[130:133], v[196:199], v[126:129]
	v_mfma_f32_16x16x32_bf16 v[126:129], v[134:137], v[200:203], v[126:129]
	v_mfma_f32_16x16x32_bf16 v[110:113], v[130:133], v[204:207], v[110:113]
	v_mfma_f32_16x16x32_bf16 v[110:113], v[134:137], v[208:211], v[110:113]
	v_mfma_f32_16x16x32_bf16 v[94:97], v[130:133], v[212:215], v[94:97]
	v_mfma_f32_16x16x32_bf16 v[94:97], v[134:137], v[220:223], v[94:97]
	v_mfma_f32_16x16x32_bf16 v[78:81], v[130:133], v[224:227], v[78:81]
	v_mfma_f32_16x16x32_bf16 v[78:81], v[134:137], v[228:231], v[78:81]
	v_mfma_f32_16x16x32_bf16 v[74:77], v[138:141], v[224:227], v[74:77]
	v_mfma_f32_16x16x32_bf16 v[74:77], v[142:145], v[228:231], v[74:77]
	v_mfma_f32_16x16x32_bf16 v[90:93], v[138:141], v[212:215], v[90:93]
	v_mfma_f32_16x16x32_bf16 v[90:93], v[142:145], v[220:223], v[90:93]
	v_mfma_f32_16x16x32_bf16 v[106:109], v[138:141], v[204:207], v[106:109]
	v_mfma_f32_16x16x32_bf16 v[106:109], v[142:145], v[208:211], v[106:109]
	v_mfma_f32_16x16x32_bf16 v[122:125], v[138:141], v[196:199], v[122:125]
	v_mfma_f32_16x16x32_bf16 v[122:125], v[142:145], v[200:203], v[122:125]
	v_mfma_f32_16x16x32_bf16 v[118:121], v[162:165], v[196:199], v[118:121]
	v_mfma_f32_16x16x32_bf16 v[118:121], v[180:183], v[200:203], v[118:121]
	v_mfma_f32_16x16x32_bf16 v[102:105], v[162:165], v[204:207], v[102:105]
	v_mfma_f32_16x16x32_bf16 v[102:105], v[180:183], v[208:211], v[102:105]
	v_mfma_f32_16x16x32_bf16 v[86:89], v[162:165], v[212:215], v[86:89]
	v_mfma_f32_16x16x32_bf16 v[86:89], v[180:183], v[220:223], v[86:89]
	v_mfma_f32_16x16x32_bf16 v[70:73], v[162:165], v[224:227], v[70:73]
	v_mfma_f32_16x16x32_bf16 v[70:73], v[180:183], v[228:231], v[70:73]
	v_mfma_f32_16x16x32_bf16 v[66:69], v[184:187], v[224:227], v[66:69]
	v_mfma_f32_16x16x32_bf16 v[66:69], v[188:191], v[228:231], v[66:69]
	v_mfma_f32_16x16x32_bf16 v[82:85], v[184:187], v[212:215], v[82:85]
	v_mfma_f32_16x16x32_bf16 v[82:85], v[188:191], v[220:223], v[82:85]
	v_mfma_f32_16x16x32_bf16 v[98:101], v[184:187], v[204:207], v[98:101]
	v_mfma_f32_16x16x32_bf16 v[98:101], v[188:191], v[208:211], v[98:101]
	v_mfma_f32_16x16x32_bf16 v[114:117], v[184:187], v[196:199], v[114:117]
	v_mfma_f32_16x16x32_bf16 v[114:117], v[188:191], v[200:203], v[114:117]
	s_setprio 0
	s_waitcnt vmcnt(8)
	s_barrier
	ds_read_b128 v[196:199], v179 offset:49152
	ds_read_b128 v[200:203], v179 offset:50176
	ds_read_b128 v[204:207], v179 offset:51200
	ds_read_b128 v[208:211], v179 offset:52224
	ds_read_b128 v[212:215], v179 offset:53248
	ds_read_b128 v[220:223], v179 offset:54272
	ds_read_b128 v[224:227], v179 offset:55296
	ds_read_b128 v[228:231], v179 offset:56320
	s_add_u32 s60, s40, 0x80
	s_addc_u32 s61, s41, 0
	s_add_u32 vcc_lo, s60, 0x100000
	s_addc_u32 vcc_hi, s61, 0
	s_add_i32 m0, s24, 0x18000
	s_nop 0
	global_load_lds_dwordx4 v148, s[60:61]
	s_add_i32 m0, s24, 0x1a000
	s_nop 0
	global_load_lds_dwordx4 v152, s[60:61]
	s_add_i32 m0, s24, 0x1c000
	s_nop 0
	global_load_lds_dwordx4 v148, vcc
	s_add_i32 m0, s24, 0x1e000
	s_nop 0
	global_load_lds_dwordx4 v152, vcc
	s_add_u32 s60, s42, 0x80
	s_addc_u32 s61, s43, 0
	s_add_i32 m0, s24, 0x8000
	s_nop 0
	global_load_lds_dwordx4 v146, s[60:61]
	s_add_i32 m0, s24, 0xa000
	s_nop 0
	global_load_lds_dwordx4 v150, s[60:61]
	s_waitcnt lgkmcnt(0)
	s_setprio 1
	v_mfma_f32_16x16x32_bf16 v[62:65], v[130:133], v[196:199], v[62:65]
	v_mfma_f32_16x16x32_bf16 v[62:65], v[134:137], v[200:203], v[62:65]
	v_mfma_f32_16x16x32_bf16 v[46:49], v[130:133], v[204:207], v[46:49]
	v_mfma_f32_16x16x32_bf16 v[46:49], v[134:137], v[208:211], v[46:49]
	v_mfma_f32_16x16x32_bf16 v[30:33], v[130:133], v[212:215], v[30:33]
	v_mfma_f32_16x16x32_bf16 v[30:33], v[134:137], v[220:223], v[30:33]
	v_mfma_f32_16x16x32_bf16 v[14:17], v[130:133], v[224:227], v[14:17]
	v_mfma_f32_16x16x32_bf16 v[14:17], v[134:137], v[228:231], v[14:17]
	v_mfma_f32_16x16x32_bf16 v[10:13], v[138:141], v[224:227], v[10:13]
	v_mfma_f32_16x16x32_bf16 v[10:13], v[142:145], v[228:231], v[10:13]
	v_mfma_f32_16x16x32_bf16 v[26:29], v[138:141], v[212:215], v[26:29]
	v_mfma_f32_16x16x32_bf16 v[26:29], v[142:145], v[220:223], v[26:29]
	v_mfma_f32_16x16x32_bf16 v[42:45], v[138:141], v[204:207], v[42:45]
	v_mfma_f32_16x16x32_bf16 v[42:45], v[142:145], v[208:211], v[42:45]
	v_mfma_f32_16x16x32_bf16 v[58:61], v[138:141], v[196:199], v[58:61]
	v_mfma_f32_16x16x32_bf16 v[58:61], v[142:145], v[200:203], v[58:61]
	v_mfma_f32_16x16x32_bf16 v[54:57], v[162:165], v[196:199], v[54:57]
	v_mfma_f32_16x16x32_bf16 v[54:57], v[180:183], v[200:203], v[54:57]
	v_mfma_f32_16x16x32_bf16 v[38:41], v[162:165], v[204:207], v[38:41]
	v_mfma_f32_16x16x32_bf16 v[38:41], v[180:183], v[208:211], v[38:41]
	v_mfma_f32_16x16x32_bf16 v[22:25], v[162:165], v[212:215], v[22:25]
	v_mfma_f32_16x16x32_bf16 v[22:25], v[180:183], v[220:223], v[22:25]
	v_mfma_f32_16x16x32_bf16 v[6:9], v[162:165], v[224:227], v[6:9]
	v_mfma_f32_16x16x32_bf16 v[6:9], v[180:183], v[228:231], v[6:9]
	v_mfma_f32_16x16x32_bf16 v[2:5], v[184:187], v[224:227], v[2:5]
	v_mfma_f32_16x16x32_bf16 v[2:5], v[188:191], v[228:231], v[2:5]
	v_mfma_f32_16x16x32_bf16 v[18:21], v[184:187], v[212:215], v[18:21]
	v_mfma_f32_16x16x32_bf16 v[18:21], v[188:191], v[220:223], v[18:21]
	v_mfma_f32_16x16x32_bf16 v[34:37], v[184:187], v[204:207], v[34:37]
	v_mfma_f32_16x16x32_bf16 v[34:37], v[188:191], v[208:211], v[34:37]
	v_mfma_f32_16x16x32_bf16 v[50:53], v[184:187], v[196:199], v[50:53]
	v_mfma_f32_16x16x32_bf16 v[50:53], v[188:191], v[200:203], v[50:53]
	s_setprio 0
	s_waitcnt vmcnt(8)
	s_barrier
	s_add_i32 s58, s58, 2
	s_add_u32 s36, s36, 0x100
	s_addc_u32 s37, s37, 0
	s_add_u32 s56, s56, 0x100
	s_addc_u32 s57, s57, 0
	s_cmp_gt_u32 s58, 61
	s_cbranch_scc0 .LBB0_1251
	s_branch .Lf1_exit
; #define PG8_STAGE(bufoff, gbase, voff) do { _Pragma("unroll") for (int _i = 0; _i < 2; ++_i) \
;         __builtin_amdgcn_global_load_lds((const unsigned*)((const char*)(gbase) + (voff)[_i]), (PG8_LAS unsigned*)(lds + (bufoff) + ldsw + _i * 8192), 16, 0, 0); } while (0)
; #define PG8_LDA(dst, b, h) do { _Pragma("unroll") for (int m = 0; m < 4; ++m) _Pragma("unroll") for (int k = 0; k < 2; ++k) dst[m][k] = *(const PG8_LAS bf16x8*)(lds + PG8_SA(b, h) + aoff + m * 2048 + k * 1024); } while (0)
; #define PG8_LDB(dst, b, h) do { _Pragma("unroll") for (int n = 0; n < 2; ++n) _Pragma("unroll") for (int k = 0; k < 2; ++k) dst[n][k] = *(const PG8_LAS bf16x8*)(lds + PG8_SB(b, h) + boff + n * 2048 + k * 1024); } while (0)
; #define PG8_MMA(ai, bj, At, Bt) do { __builtin_amdgcn_s_setprio(1); _Pragma("unroll") for (int m = 0; m < 4; ++m) _Pragma("unroll") for (int n = 0; n < 2; ++n) _Pragma("unroll") for (int k = 0; k < 2; ++k) \
;         acc[ai][bj][m][n] = __builtin_amdgcn_mfma_f32_16x16x32_bf16(Bt[n][k], At[m][k], acc[ai][bj][m][n], 0, 0, 0); __builtin_amdgcn_s_setprio(0); } while (0)
; #define PG8_WAIT_V(n) asm volatile("s_waitcnt vmcnt(" #n ")" ::: "memory")
; #define PG8_WAIT_L(n) asm volatile("s_waitcnt lgkmcnt(" #n ")" ::: "memory")
; template <class Epi, class Sched, bool ALIGN_EPI = false, bool SP2 = false>
; __device__ __forceinline__ void gemm_phase(PG8_LAS unsigned char* lds, const Gemm g, const Sched& S, const Epi& E) {
;     ...
;             const bool last = (t == nt - 2);
;             const char* a1 = cA + (size_t)(t + 1) * kstep;
;             const char* a2 = last ? nA : cA + (size_t)(t + 2) * kstep; const char* b2 = last ? nB : cB + (size_t)(t + 2) * kstep;
;             const char* a3 = a2 + kstep; const char* b3 = b2 + kstep;
;             if (last && has_next) S.a_ready(nxt);
;             if constexpr (Epi::MIDK) { if (t == (nt >> 1)) { E.midk(acc, wr, fr); asm volatile("s_waitcnt lgkmcnt(0)" ::: "memory"); } }
;             if constexpr (SP2) {
;             PG8_LDB(B0, 0, 0); PG8_LDB(B1, 0, 1); PG8_SCHED; PG8_LDA(At, 0, 0); PG8_STAGE(PG8_SA(1, 1), a1 + hstep, voffA);
;             PG8_WAIT_V(8); PG8_WAIT_L(0); PG8_BAR; PG8_MMA(0, 0, At, B0); PG8_MMA(0, 1, At, B1); PG8_BAR; PG8_SCHED;
;             PG8_LDA(At, 0, 1); PG8_STAGE(PG8_SB(0, 0), b2, voffB); PG8_STAGE(PG8_SB(0, 1), b2 + hstep, voffB); PG8_STAGE(PG8_SA(0, 0), a2, voffA);
.Lf1_h1:
	ds_read_b128 v[130:133], v177
	ds_read_b128 v[134:137], v177 offset:1024
	ds_read_b128 v[138:141], v177 offset:2048
	ds_read_b128 v[142:145], v177 offset:3072
	ds_read_b128 v[162:165], v178
	ds_read_b128 v[180:183], v178 offset:1024
	ds_read_b128 v[184:187], v178 offset:2048
	ds_read_b128 v[188:191], v178 offset:3072
	s_add_u32 s40, s36, 0xfff00080
	s_addc_u32 s41, s37, -1
	s_cmp_eq_u32 s58, 60
	s_cselect_b32 s43, s15, s41
	s_cselect_b32 s42, s17, s40
	s_cselect_b32 s41, s54, s57
	s_cselect_b32 s40, s55, s56
	ds_read_b128 v[196:199], v179
	ds_read_b128 v[200:203], v179 offset:1024
	ds_read_b128 v[204:207], v179 offset:2048
	ds_read_b128 v[208:211], v179 offset:3072
	ds_read_b128 v[212:215], v179 offset:4096
	ds_read_b128 v[220:223], v179 offset:5120
	ds_read_b128 v[224:227], v179 offset:6144
	ds_read_b128 v[228:231], v179 offset:7168
	s_add_i32 m0, s24, 0xc000
	s_nop 0
	global_load_lds_dwordx4 v146, s[36:37]
	s_add_i32 m0, s24, 0xe000
	s_nop 0
	global_load_lds_dwordx4 v150, s[36:37]
	s_sleep 2
	s_waitcnt lgkmcnt(0)
	s_waitcnt vmcnt(8)
	s_barrier
	s_setprio 2
	v_mfma_f32_16x16x32_bf16 v[126:129], v[130:133], v[196:199], v[126:129]
	v_mfma_f32_16x16x32_bf16 v[126:129], v[134:137], v[200:203], v[126:129]
	v_mfma_f32_16x16x32_bf16 v[110:113], v[130:133], v[204:207], v[110:113]
	v_mfma_f32_16x16x32_bf16 v[110:113], v[134:137], v[208:211], v[110:113]
	v_mfma_f32_16x16x32_bf16 v[94:97], v[130:133], v[212:215], v[94:97]
	v_mfma_f32_16x16x32_bf16 v[94:97], v[134:137], v[220:223], v[94:97]
	v_mfma_f32_16x16x32_bf16 v[78:81], v[130:133], v[224:227], v[78:81]
	v_mfma_f32_16x16x32_bf16 v[78:81], v[134:137], v[228:231], v[78:81]
	v_mfma_f32_16x16x32_bf16 v[74:77], v[138:141], v[224:227], v[74:77]
	v_mfma_f32_16x16x32_bf16 v[74:77], v[142:145], v[228:231], v[74:77]
	v_mfma_f32_16x16x32_bf16 v[90:93], v[138:141], v[212:215], v[90:93]
	v_mfma_f32_16x16x32_bf16 v[90:93], v[142:145], v[220:223], v[90:93]
	v_mfma_f32_16x16x32_bf16 v[106:109], v[138:141], v[204:207], v[106:109]
	v_mfma_f32_16x16x32_bf16 v[106:109], v[142:145], v[208:211], v[106:109]
	v_mfma_f32_16x16x32_bf16 v[122:125], v[138:141], v[196:199], v[122:125]
	v_mfma_f32_16x16x32_bf16 v[122:125], v[142:145], v[200:203], v[122:125]
	v_mfma_f32_16x16x32_bf16 v[118:121], v[162:165], v[196:199], v[118:121]
	v_mfma_f32_16x16x32_bf16 v[118:121], v[180:183], v[200:203], v[118:121]
	v_mfma_f32_16x16x32_bf16 v[102:105], v[162:165], v[204:207], v[102:105]
	v_mfma_f32_16x16x32_bf16 v[102:105], v[180:183], v[208:211], v[102:105]
	v_mfma_f32_16x16x32_bf16 v[86:89], v[162:165], v[212:215], v[86:89]
	v_mfma_f32_16x16x32_bf16 v[86:89], v[180:183], v[220:223], v[86:89]
	v_mfma_f32_16x16x32_bf16 v[70:73], v[162:165], v[224:227], v[70:73]
	v_mfma_f32_16x16x32_bf16 v[70:73], v[180:183], v[228:231], v[70:73]
	v_mfma_f32_16x16x32_bf16 v[66:69], v[184:187], v[224:227], v[66:69]
	v_mfma_f32_16x16x32_bf16 v[66:69], v[188:191], v[228:231], v[66:69]
	v_mfma_f32_16x16x32_bf16 v[82:85], v[184:187], v[212:215], v[82:85]
	v_mfma_f32_16x16x32_bf16 v[82:85], v[188:191], v[220:223], v[82:85]
	v_mfma_f32_16x16x32_bf16 v[98:101], v[184:187], v[204:207], v[98:101]
	v_mfma_f32_16x16x32_bf16 v[98:101], v[188:191], v[208:211], v[98:101]
	v_mfma_f32_16x16x32_bf16 v[114:117], v[184:187], v[196:199], v[114:117]
	v_mfma_f32_16x16x32_bf16 v[114:117], v[188:191], v[200:203], v[114:117]
	s_setprio 0
	ds_read_b128 v[196:199], v179 offset:16384
	ds_read_b128 v[200:203], v179 offset:17408
	ds_read_b128 v[204:207], v179 offset:18432
	ds_read_b128 v[208:211], v179 offset:19456
	ds_read_b128 v[212:215], v179 offset:20480
	ds_read_b128 v[220:223], v179 offset:21504
	ds_read_b128 v[224:227], v179 offset:22528
	ds_read_b128 v[228:231], v179 offset:23552
	s_add_u32 vcc_lo, s40, 0x100000
	s_addc_u32 vcc_hi, s41, 0
	s_add_i32 m0, s24, 0x10000
	s_nop 0
	global_load_lds_dwordx4 v148, s[40:41]
	s_add_i32 m0, s24, 0x12000
	s_nop 0
	global_load_lds_dwordx4 v152, s[40:41]
	s_add_i32 m0, s24, 0x14000
	s_nop 0
	global_load_lds_dwordx4 v148, vcc
	s_add_i32 m0, s24, 0x16000
	s_nop 0
	global_load_lds_dwordx4 v152, vcc
	s_mov_b32 m0, s24
	s_nop 0
	global_load_lds_dwordx4 v146, s[42:43]
	s_add_i32 m0, s24, 0x2000
	s_nop 0
	global_load_lds_dwordx4 v150, s[42:43]
	s_sleep 2
	s_waitcnt lgkmcnt(0)
	s_waitcnt vmcnt(8)
	s_barrier
; #define PG8_STAGE(bufoff, gbase, voff) do { _Pragma("unroll") for (int _i = 0; _i < 2; ++_i) \
;         __builtin_amdgcn_global_load_lds((const unsigned*)((const char*)(gbase) + (voff)[_i]), (PG8_LAS unsigned*)(lds + (bufoff) + ldsw + _i * 8192), 16, 0, 0); } while (0)
; #define PG8_LDA(dst, b, h) do { _Pragma("unroll") for (int m = 0; m < 4; ++m) _Pragma("unroll") for (int k = 0; k < 2; ++k) dst[m][k] = *(const PG8_LAS bf16x8*)(lds + PG8_SA(b, h) + aoff + m * 2048 + k * 1024); } while (0)
; #define PG8_LDB(dst, b, h) do { _Pragma("unroll") for (int n = 0; n < 2; ++n) _Pragma("unroll") for (int k = 0; k < 2; ++k) dst[n][k] = *(const PG8_LAS bf16x8*)(lds + PG8_SB(b, h) + boff + n * 2048 + k * 1024); } while (0)
; #define PG8_MMA(ai, bj, At, Bt) do { __builtin_amdgcn_s_setprio(1); _Pragma("unroll") for (int m = 0; m < 4; ++m) _Pragma("unroll") for (int n = 0; n < 2; ++n) _Pragma("unroll") for (int k = 0; k < 2; ++k) \
;         acc[ai][bj][m][n] = __builtin_amdgcn_mfma_f32_16x16x32_bf16(Bt[n][k], At[m][k], acc[ai][bj][m][n], 0, 0, 0); __builtin_amdgcn_s_setprio(0); } while (0)
; #define PG8_WAIT_V(n) asm volatile("s_waitcnt vmcnt(" #n ")" ::: "memory")
; #define PG8_WAIT_L(n) asm volatile("s_waitcnt lgkmcnt(" #n ")" ::: "memory")
; #define PG8_BAR __builtin_amdgcn_s_barrier()
; #define PG8_SCHED __builtin_amdgcn_sched_barrier(0)
; template <class Epi, class Sched, bool ALIGN_EPI = false, bool SP2 = false>
; __device__ __forceinline__ void gemm_phase(PG8_LAS unsigned char* lds, const Gemm g, const Sched& S, const Epi& E) {
;     ...
;             PG8_WAIT_V(8); PG8_WAIT_L(0); PG8_BAR; PG8_MMA(1, 0, At, B0); PG8_MMA(1, 1, At, B1); PG8_BAR; PG8_SCHED;
;             PG8_LDB(B0, 1, 0); PG8_LDB(B1, 1, 1); PG8_SCHED; PG8_LDA(At, 1, 0); PG8_STAGE(PG8_SA(0, 1), a2 + hstep, voffA);
;             PG8_WAIT_V(8); PG8_WAIT_L(0); PG8_BAR; PG8_MMA(0, 0, At, B0); PG8_MMA(0, 1, At, B1); PG8_BAR; PG8_SCHED;
	s_setprio 2
	v_mfma_f32_16x16x32_bf16 v[62:65], v[130:133], v[196:199], v[62:65]
	v_mfma_f32_16x16x32_bf16 v[62:65], v[134:137], v[200:203], v[62:65]
	v_mfma_f32_16x16x32_bf16 v[46:49], v[130:133], v[204:207], v[46:49]
	v_mfma_f32_16x16x32_bf16 v[46:49], v[134:137], v[208:211], v[46:49]
	v_mfma_f32_16x16x32_bf16 v[30:33], v[130:133], v[212:215], v[30:33]
	v_mfma_f32_16x16x32_bf16 v[30:33], v[134:137], v[220:223], v[30:33]
	v_mfma_f32_16x16x32_bf16 v[14:17], v[130:133], v[224:227], v[14:17]
	v_mfma_f32_16x16x32_bf16 v[14:17], v[134:137], v[228:231], v[14:17]
	v_mfma_f32_16x16x32_bf16 v[10:13], v[138:141], v[224:227], v[10:13]
	v_mfma_f32_16x16x32_bf16 v[10:13], v[142:145], v[228:231], v[10:13]
	v_mfma_f32_16x16x32_bf16 v[26:29], v[138:141], v[212:215], v[26:29]
	v_mfma_f32_16x16x32_bf16 v[26:29], v[142:145], v[220:223], v[26:29]
	v_mfma_f32_16x16x32_bf16 v[42:45], v[138:141], v[204:207], v[42:45]
	v_mfma_f32_16x16x32_bf16 v[42:45], v[142:145], v[208:211], v[42:45]
	v_mfma_f32_16x16x32_bf16 v[58:61], v[138:141], v[196:199], v[58:61]
	v_mfma_f32_16x16x32_bf16 v[58:61], v[142:145], v[200:203], v[58:61]
	v_mfma_f32_16x16x32_bf16 v[54:57], v[162:165], v[196:199], v[54:57]
	v_mfma_f32_16x16x32_bf16 v[54:57], v[180:183], v[200:203], v[54:57]
	v_mfma_f32_16x16x32_bf16 v[38:41], v[162:165], v[204:207], v[38:41]
	v_mfma_f32_16x16x32_bf16 v[38:41], v[180:183], v[208:211], v[38:41]
	v_mfma_f32_16x16x32_bf16 v[22:25], v[162:165], v[212:215], v[22:25]
	v_mfma_f32_16x16x32_bf16 v[22:25], v[180:183], v[220:223], v[22:25]
	v_mfma_f32_16x16x32_bf16 v[6:9], v[162:165], v[224:227], v[6:9]
	v_mfma_f32_16x16x32_bf16 v[6:9], v[180:183], v[228:231], v[6:9]
	v_mfma_f32_16x16x32_bf16 v[2:5], v[184:187], v[224:227], v[2:5]
	v_mfma_f32_16x16x32_bf16 v[2:5], v[188:191], v[228:231], v[2:5]
	v_mfma_f32_16x16x32_bf16 v[18:21], v[184:187], v[212:215], v[18:21]
	v_mfma_f32_16x16x32_bf16 v[18:21], v[188:191], v[220:223], v[18:21]
	v_mfma_f32_16x16x32_bf16 v[34:37], v[184:187], v[204:207], v[34:37]
	v_mfma_f32_16x16x32_bf16 v[34:37], v[188:191], v[208:211], v[34:37]
	v_mfma_f32_16x16x32_bf16 v[50:53], v[184:187], v[196:199], v[50:53]
	v_mfma_f32_16x16x32_bf16 v[50:53], v[188:191], v[200:203], v[50:53]
	s_setprio 0
	s_add_i32 s59, 0, 0x18000
	s_add_i32 s60, 0, 0x1c000
	v_add_u32_e32 v142, s59, v166
	v_add_u32_e32 v188, s60, v166
	ds_read_b128 v[130:133], v142
	ds_read_b128 v[134:137], v142 offset:1024
	ds_read_b128 v[138:141], v142 offset:2048
	ds_read_b128 v[142:145], v142 offset:3072
	ds_read_b128 v[162:165], v188
	ds_read_b128 v[180:183], v188 offset:1024
	ds_read_b128 v[184:187], v188 offset:2048
	ds_read_b128 v[188:191], v188 offset:3072
	ds_read_b128 v[196:199], v179 offset:32768
	ds_read_b128 v[200:203], v179 offset:33792
	ds_read_b128 v[204:207], v179 offset:34816
	ds_read_b128 v[208:211], v179 offset:35840
	ds_read_b128 v[212:215], v179 offset:36864
	ds_read_b128 v[220:223], v179 offset:37888
	ds_read_b128 v[224:227], v179 offset:38912
	ds_read_b128 v[228:231], v179 offset:39936
	s_add_u32 vcc_lo, s42, 0x100000
	s_addc_u32 vcc_hi, s43, 0
	s_add_i32 m0, s24, 0x4000
	s_nop 0
	global_load_lds_dwordx4 v146, vcc
	s_add_i32 m0, s24, 0x6000
	s_nop 0
	global_load_lds_dwordx4 v150, vcc
	s_sleep 2
	s_waitcnt lgkmcnt(0)
	s_waitcnt vmcnt(8)
	s_barrier
; #define PG8_STAGE(bufoff, gbase, voff) do { _Pragma("unroll") for (int _i = 0; _i < 2; ++_i) \
;         __builtin_amdgcn_global_load_lds((const unsigned*)((const char*)(gbase) + (voff)[_i]), (PG8_LAS unsigned*)(lds + (bufoff) + ldsw + _i * 8192), 16, 0, 0); } while (0)
; #define PG8_LDA(dst, b, h) do { _Pragma("unroll") for (int m = 0; m < 4; ++m) _Pragma("unroll") for (int k = 0; k < 2; ++k) dst[m][k] = *(const PG8_LAS bf16x8*)(lds + PG8_SA(b, h) + aoff + m * 2048 + k * 1024); } while (0)
; #define PG8_MMA(ai, bj, At, Bt) do { __builtin_amdgcn_s_setprio(1); _Pragma("unroll") for (int m = 0; m < 4; ++m) _Pragma("unroll") for (int n = 0; n < 2; ++n) _Pragma("unroll") for (int k = 0; k < 2; ++k) \
;         acc[ai][bj][m][n] = __builtin_amdgcn_mfma_f32_16x16x32_bf16(Bt[n][k], At[m][k], acc[ai][bj][m][n], 0, 0, 0); __builtin_amdgcn_s_setprio(0); } while (0)
; #define PG8_WAIT_V(n) asm volatile("s_waitcnt vmcnt(" #n ")" ::: "memory")
; #define PG8_WAIT_L(n) asm volatile("s_waitcnt lgkmcnt(" #n ")" ::: "memory")
; #define PG8_BAR __builtin_amdgcn_s_barrier()
; #define PG8_SCHED __builtin_amdgcn_sched_barrier(0)
; template <class Epi, class Sched, bool ALIGN_EPI = false, bool SP2 = false>
; __device__ __forceinline__ void gemm_phase(PG8_LAS unsigned char* lds, const Gemm g, const Sched& S, const Epi& E) {
;     ...
;         for (int t = 0; t < nt; t += 2) {
;             const bool last = (t == nt - 2);
;             const char* a1 = cA + (size_t)(t + 1) * kstep;
;             const char* a2 = last ? nA : cA + (size_t)(t + 2) * kstep; const char* b2 = last ? nB : cB + (size_t)(t + 2) * kstep;
;             const char* a3 = a2 + kstep; const char* b3 = b2 + kstep;
;     ...
;             PG8_WAIT_V(8); PG8_WAIT_L(0); PG8_BAR; PG8_MMA(0, 0, At, B0); PG8_MMA(0, 1, At, B1); PG8_BAR; PG8_SCHED;
;             PG8_LDA(At, 1, 1); PG8_STAGE(PG8_SB(1, 0), b3, voffB); PG8_STAGE(PG8_SB(1, 1), b3 + hstep, voffB); PG8_STAGE(PG8_SA(1, 0), a3, voffA);
;             PG8_WAIT_V(8); PG8_WAIT_L(0); PG8_BAR; PG8_MMA(1, 0, At, B0); PG8_MMA(1, 1, At, B1); PG8_BAR; PG8_SCHED;
	s_setprio 2
	v_mfma_f32_16x16x32_bf16 v[126:129], v[130:133], v[196:199], v[126:129]
	v_mfma_f32_16x16x32_bf16 v[126:129], v[134:137], v[200:203], v[126:129]
	v_mfma_f32_16x16x32_bf16 v[110:113], v[130:133], v[204:207], v[110:113]
	v_mfma_f32_16x16x32_bf16 v[110:113], v[134:137], v[208:211], v[110:113]
	v_mfma_f32_16x16x32_bf16 v[94:97], v[130:133], v[212:215], v[94:97]
	v_mfma_f32_16x16x32_bf16 v[94:97], v[134:137], v[220:223], v[94:97]
	v_mfma_f32_16x16x32_bf16 v[78:81], v[130:133], v[224:227], v[78:81]
	v_mfma_f32_16x16x32_bf16 v[78:81], v[134:137], v[228:231], v[78:81]
	v_mfma_f32_16x16x32_bf16 v[74:77], v[138:141], v[224:227], v[74:77]
	v_mfma_f32_16x16x32_bf16 v[74:77], v[142:145], v[228:231], v[74:77]
	v_mfma_f32_16x16x32_bf16 v[90:93], v[138:141], v[212:215], v[90:93]
	v_mfma_f32_16x16x32_bf16 v[90:93], v[142:145], v[220:223], v[90:93]
	v_mfma_f32_16x16x32_bf16 v[106:109], v[138:141], v[204:207], v[106:109]
	v_mfma_f32_16x16x32_bf16 v[106:109], v[142:145], v[208:211], v[106:109]
	v_mfma_f32_16x16x32_bf16 v[122:125], v[138:141], v[196:199], v[122:125]
	v_mfma_f32_16x16x32_bf16 v[122:125], v[142:145], v[200:203], v[122:125]
	v_mfma_f32_16x16x32_bf16 v[118:121], v[162:165], v[196:199], v[118:121]
	v_mfma_f32_16x16x32_bf16 v[118:121], v[180:183], v[200:203], v[118:121]
	v_mfma_f32_16x16x32_bf16 v[102:105], v[162:165], v[204:207], v[102:105]
	v_mfma_f32_16x16x32_bf16 v[102:105], v[180:183], v[208:211], v[102:105]
	v_mfma_f32_16x16x32_bf16 v[86:89], v[162:165], v[212:215], v[86:89]
	v_mfma_f32_16x16x32_bf16 v[86:89], v[180:183], v[220:223], v[86:89]
	v_mfma_f32_16x16x32_bf16 v[70:73], v[162:165], v[224:227], v[70:73]
	v_mfma_f32_16x16x32_bf16 v[70:73], v[180:183], v[228:231], v[70:73]
	v_mfma_f32_16x16x32_bf16 v[66:69], v[184:187], v[224:227], v[66:69]
	v_mfma_f32_16x16x32_bf16 v[66:69], v[188:191], v[228:231], v[66:69]
	v_mfma_f32_16x16x32_bf16 v[82:85], v[184:187], v[212:215], v[82:85]
	v_mfma_f32_16x16x32_bf16 v[82:85], v[188:191], v[220:223], v[82:85]
	v_mfma_f32_16x16x32_bf16 v[98:101], v[184:187], v[204:207], v[98:101]
	v_mfma_f32_16x16x32_bf16 v[98:101], v[188:191], v[208:211], v[98:101]
	v_mfma_f32_16x16x32_bf16 v[114:117], v[184:187], v[196:199], v[114:117]
	v_mfma_f32_16x16x32_bf16 v[114:117], v[188:191], v[200:203], v[114:117]
	s_setprio 0
	ds_read_b128 v[196:199], v179 offset:49152
	ds_read_b128 v[200:203], v179 offset:50176
	ds_read_b128 v[204:207], v179 offset:51200
	ds_read_b128 v[208:211], v179 offset:52224
	ds_read_b128 v[212:215], v179 offset:53248
	ds_read_b128 v[220:223], v179 offset:54272
	ds_read_b128 v[224:227], v179 offset:55296
	ds_read_b128 v[228:231], v179 offset:56320
	s_add_u32 s60, s40, 0x80
	s_addc_u32 s61, s41, 0
	s_add_u32 vcc_lo, s60, 0x100000
	s_addc_u32 vcc_hi, s61, 0
	s_add_i32 m0, s24, 0x18000
	s_nop 0
	global_load_lds_dwordx4 v148, s[60:61]
	s_add_i32 m0, s24, 0x1a000
	s_nop 0
	global_load_lds_dwordx4 v152, s[60:61]
	s_add_i32 m0, s24, 0x1c000
	s_nop 0
	global_load_lds_dwordx4 v148, vcc
	s_add_i32 m0, s24, 0x1e000
	s_nop 0
	global_load_lds_dwordx4 v152, vcc
	s_add_u32 s60, s42, 0x80
	s_addc_u32 s61, s43, 0
	s_add_i32 m0, s24, 0x8000
	s_nop 0
	global_load_lds_dwordx4 v146, s[60:61]
	s_add_i32 m0, s24, 0xa000
	s_nop 0
	global_load_lds_dwordx4 v150, s[60:61]
	s_sleep 2
	s_waitcnt lgkmcnt(0)
	s_waitcnt vmcnt(8)
	s_barrier
	s_setprio 2
	v_mfma_f32_16x16x32_bf16 v[62:65], v[130:133], v[196:199], v[62:65]
	v_mfma_f32_16x16x32_bf16 v[62:65], v[134:137], v[200:203], v[62:65]
	v_mfma_f32_16x16x32_bf16 v[46:49], v[130:133], v[204:207], v[46:49]
	v_mfma_f32_16x16x32_bf16 v[46:49], v[134:137], v[208:211], v[46:49]
	v_mfma_f32_16x16x32_bf16 v[30:33], v[130:133], v[212:215], v[30:33]
	v_mfma_f32_16x16x32_bf16 v[30:33], v[134:137], v[220:223], v[30:33]
	v_mfma_f32_16x16x32_bf16 v[14:17], v[130:133], v[224:227], v[14:17]
	v_mfma_f32_16x16x32_bf16 v[14:17], v[134:137], v[228:231], v[14:17]
	v_mfma_f32_16x16x32_bf16 v[10:13], v[138:141], v[224:227], v[10:13]
	v_mfma_f32_16x16x32_bf16 v[10:13], v[142:145], v[228:231], v[10:13]
	v_mfma_f32_16x16x32_bf16 v[26:29], v[138:141], v[212:215], v[26:29]
	v_mfma_f32_16x16x32_bf16 v[26:29], v[142:145], v[220:223], v[26:29]
	v_mfma_f32_16x16x32_bf16 v[42:45], v[138:141], v[204:207], v[42:45]
	v_mfma_f32_16x16x32_bf16 v[42:45], v[142:145], v[208:211], v[42:45]
	v_mfma_f32_16x16x32_bf16 v[58:61], v[138:141], v[196:199], v[58:61]
	v_mfma_f32_16x16x32_bf16 v[58:61], v[142:145], v[200:203], v[58:61]
	v_mfma_f32_16x16x32_bf16 v[54:57], v[162:165], v[196:199], v[54:57]
	v_mfma_f32_16x16x32_bf16 v[54:57], v[180:183], v[200:203], v[54:57]
	v_mfma_f32_16x16x32_bf16 v[38:41], v[162:165], v[204:207], v[38:41]
	v_mfma_f32_16x16x32_bf16 v[38:41], v[180:183], v[208:211], v[38:41]
	v_mfma_f32_16x16x32_bf16 v[22:25], v[162:165], v[212:215], v[22:25]
	v_mfma_f32_16x16x32_bf16 v[22:25], v[180:183], v[220:223], v[22:25]
	v_mfma_f32_16x16x32_bf16 v[6:9], v[162:165], v[224:227], v[6:9]
	v_mfma_f32_16x16x32_bf16 v[6:9], v[180:183], v[228:231], v[6:9]
	v_mfma_f32_16x16x32_bf16 v[2:5], v[184:187], v[224:227], v[2:5]
	v_mfma_f32_16x16x32_bf16 v[2:5], v[188:191], v[228:231], v[2:5]
	v_mfma_f32_16x16x32_bf16 v[18:21], v[184:187], v[212:215], v[18:21]
	v_mfma_f32_16x16x32_bf16 v[18:21], v[188:191], v[220:223], v[18:21]
	v_mfma_f32_16x16x32_bf16 v[34:37], v[184:187], v[204:207], v[34:37]
	v_mfma_f32_16x16x32_bf16 v[34:37], v[188:191], v[208:211], v[34:37]
	v_mfma_f32_16x16x32_bf16 v[50:53], v[184:187], v[196:199], v[50:53]
	v_mfma_f32_16x16x32_bf16 v[50:53], v[188:191], v[200:203], v[50:53]
	s_setprio 0
	s_add_i32 s58, s58, 2
	s_add_u32 s36, s36, 0x100
	s_addc_u32 s37, s37, 0
	s_add_u32 s56, s56, 0x100
	s_addc_u32 s57, s57, 0
	s_cmp_gt_u32 s58, 61
	s_cbranch_scc0 .Lf1_h1

; #define PG8_STAGE(bufoff, gbase, voff) do { _Pragma("unroll") for (int _i = 0; _i < 2; ++_i) \
;         __builtin_amdgcn_global_load_lds((const unsigned*)((const char*)(gbase) + (voff)[_i]), (PG8_LAS unsigned*)(lds + (bufoff) + ldsw + _i * 8192), 16, 0, 0); } while (0)
; #define PG8_LDA(dst, b, h) do { _Pragma("unroll") for (int m = 0; m < 4; ++m) _Pragma("unroll") for (int k = 0; k < 2; ++k) dst[m][k] = *(const PG8_LAS bf16x8*)(lds + PG8_SA(b, h) + aoff + m * 2048 + k * 1024); } while (0)
; #define PG8_LDB(dst, b, h) do { _Pragma("unroll") for (int n = 0; n < 2; ++n) _Pragma("unroll") for (int k = 0; k < 2; ++k) dst[n][k] = *(const PG8_LAS bf16x8*)(lds + PG8_SB(b, h) + boff + n * 2048 + k * 1024); } while (0)
; #define PG8_MMA(ai, bj, At, Bt) do { __builtin_amdgcn_s_setprio(1); _Pragma("unroll") for (int m = 0; m < 4; ++m) _Pragma("unroll") for (int n = 0; n < 2; ++n) _Pragma("unroll") for (int k = 0; k < 2; ++k) \
;         acc[ai][bj][m][n] = __builtin_amdgcn_mfma_f32_16x16x32_bf16(Bt[n][k], At[m][k], acc[ai][bj][m][n], 0, 0, 0); __builtin_amdgcn_s_setprio(0); } while (0)
; #define PG8_WAIT_V(n) asm volatile("s_waitcnt vmcnt(" #n ")" ::: "memory")
; #define PG8_WAIT_L(n) asm volatile("s_waitcnt lgkmcnt(" #n ")" ::: "memory")
; #define PG8_BAR __builtin_amdgcn_s_barrier()
; #define PG8_SCHED __builtin_amdgcn_sched_barrier(0)
; template <class Epi, class Sched, bool ALIGN_EPI = false, bool SP2 = false>
; __device__ __forceinline__ void gemm_phase(PG8_LAS unsigned char* lds, const Gemm g, const Sched& S, const Epi& E) {
;     ...
;             const bool last = (t == nt - 2);
;             const char* a1 = cA + (size_t)(t + 1) * kstep;
;             const char* a2 = last ? nA : cA + (size_t)(t + 2) * kstep; const char* b2 = last ? nB : cB + (size_t)(t + 2) * kstep;
;             const char* a3 = a2 + kstep; const char* b3 = b2 + kstep;
;     ...
;             PG8_LDB(B0, 0, 0); PG8_LDB(B1, 0, 1); PG8_SCHED; PG8_LDA(At, 0, 0); PG8_STAGE(PG8_SA(1, 1), a1 + hstep, voffA);
;             PG8_WAIT_V(8); PG8_WAIT_L(0); PG8_BAR; PG8_MMA(0, 0, At, B0); PG8_MMA(0, 1, At, B1); PG8_BAR; PG8_SCHED;
;             PG8_LDA(At, 0, 1); PG8_STAGE(PG8_SB(0, 0), b2, voffB); PG8_STAGE(PG8_SB(0, 1), b2 + hstep, voffB); PG8_STAGE(PG8_SA(0, 0), a2, voffA);
;             PG8_WAIT_V(8); PG8_WAIT_L(0); PG8_BAR; PG8_MMA(1, 0, At, B0); PG8_MMA(1, 1, At, B1); PG8_BAR; PG8_SCHED;
.LBB0_1321:
	ds_read_b128 v[128:131], v156
	ds_read_b128 v[132:135], v156 offset:1024
	ds_read_b128 v[150:153], v156 offset:2048
	ds_read_b128 v[162:165], v156 offset:3072
	ds_read_b128 v[166:169], v157
	ds_read_b128 v[170:173], v157 offset:1024
	ds_read_b128 v[174:177], v157 offset:2048
	ds_read_b128 v[178:181], v157 offset:3072
	s_add_u32 s20, s18, 0xffbfc080
	s_addc_u32 s21, s19, -1
	s_cmpk_eq_i32 s59, 0xfc
	s_cselect_b32 s23, s7, s21
	s_cselect_b32 s22, s6, s20
	s_cselect_b32 s21, s17, s58
	s_cselect_b32 s20, s16, s57
	ds_read_b128 v[182:185], v158
	ds_read_b128 v[186:189], v158 offset:1024
	ds_read_b128 v[190:193], v158 offset:2048
	ds_read_b128 v[194:197], v158 offset:3072
	ds_read_b128 v[198:201], v158 offset:4096
	ds_read_b128 v[202:205], v158 offset:5120
	ds_read_b128 v[206:209], v158 offset:6144
	ds_read_b128 v[210:213], v158 offset:7168
	s_add_i32 m0, s24, 0xc000
	s_nop 0
	global_load_lds_dwordx4 v136, s[18:19]
	s_add_i32 m0, s24, 0xe000
	s_nop 0
	global_load_lds_dwordx4 v140, s[18:19]
	s_waitcnt lgkmcnt(0)
	s_setprio 1
	v_mfma_f32_16x16x32_bf16 v[124:127], v[128:131], v[182:185], v[124:127]
	v_mfma_f32_16x16x32_bf16 v[124:127], v[132:135], v[186:189], v[124:127]
	v_mfma_f32_16x16x32_bf16 v[116:119], v[128:131], v[190:193], v[116:119]
	v_mfma_f32_16x16x32_bf16 v[116:119], v[132:135], v[194:197], v[116:119]
	v_mfma_f32_16x16x32_bf16 v[108:111], v[128:131], v[198:201], v[108:111]
	v_mfma_f32_16x16x32_bf16 v[108:111], v[132:135], v[202:205], v[108:111]
	v_mfma_f32_16x16x32_bf16 v[100:103], v[128:131], v[206:209], v[100:103]
	v_mfma_f32_16x16x32_bf16 v[100:103], v[132:135], v[210:213], v[100:103]
	v_mfma_f32_16x16x32_bf16 v[96:99], v[150:153], v[206:209], v[96:99]
	v_mfma_f32_16x16x32_bf16 v[96:99], v[162:165], v[210:213], v[96:99]
	v_mfma_f32_16x16x32_bf16 v[104:107], v[150:153], v[198:201], v[104:107]
	v_mfma_f32_16x16x32_bf16 v[104:107], v[162:165], v[202:205], v[104:107]
	v_mfma_f32_16x16x32_bf16 v[112:115], v[150:153], v[190:193], v[112:115]
	v_mfma_f32_16x16x32_bf16 v[112:115], v[162:165], v[194:197], v[112:115]
	v_mfma_f32_16x16x32_bf16 v[120:123], v[150:153], v[182:185], v[120:123]
	v_mfma_f32_16x16x32_bf16 v[120:123], v[162:165], v[186:189], v[120:123]
	v_mfma_f32_16x16x32_bf16 v[68:71], v[166:169], v[182:185], v[68:71]
	v_mfma_f32_16x16x32_bf16 v[68:71], v[170:173], v[186:189], v[68:71]
	v_mfma_f32_16x16x32_bf16 v[52:55], v[166:169], v[190:193], v[52:55]
	v_mfma_f32_16x16x32_bf16 v[52:55], v[170:173], v[194:197], v[52:55]
	v_mfma_f32_16x16x32_bf16 v[44:47], v[166:169], v[198:201], v[44:47]
	v_mfma_f32_16x16x32_bf16 v[44:47], v[170:173], v[202:205], v[44:47]
	v_mfma_f32_16x16x32_bf16 v[36:39], v[166:169], v[206:209], v[36:39]
	v_mfma_f32_16x16x32_bf16 v[36:39], v[170:173], v[210:213], v[36:39]
	v_mfma_f32_16x16x32_bf16 v[32:35], v[174:177], v[206:209], v[32:35]
	v_mfma_f32_16x16x32_bf16 v[32:35], v[178:181], v[210:213], v[32:35]
	v_mfma_f32_16x16x32_bf16 v[40:43], v[174:177], v[198:201], v[40:43]
	v_mfma_f32_16x16x32_bf16 v[40:43], v[178:181], v[202:205], v[40:43]
	v_mfma_f32_16x16x32_bf16 v[48:51], v[174:177], v[190:193], v[48:51]
	v_mfma_f32_16x16x32_bf16 v[48:51], v[178:181], v[194:197], v[48:51]
	v_mfma_f32_16x16x32_bf16 v[64:67], v[174:177], v[182:185], v[64:67]
	v_mfma_f32_16x16x32_bf16 v[64:67], v[178:181], v[186:189], v[64:67]
	s_setprio 0
	s_waitcnt vmcnt(8)
	s_barrier
	ds_read_b128 v[182:185], v158 offset:16384
	ds_read_b128 v[186:189], v158 offset:17408
	ds_read_b128 v[190:193], v158 offset:18432
	ds_read_b128 v[194:197], v158 offset:19456
	ds_read_b128 v[198:201], v158 offset:20480
	ds_read_b128 v[202:205], v158 offset:21504
	ds_read_b128 v[206:209], v158 offset:22528
	ds_read_b128 v[210:213], v158 offset:23552
	s_add_u32 vcc_lo, s20, 0x404000
	s_addc_u32 vcc_hi, s21, 0
	s_add_i32 m0, s24, 0x10000
	s_nop 0
	global_load_lds_dwordx4 v138, s[20:21]
	s_add_i32 m0, s24, 0x12000
	s_nop 0
	global_load_lds_dwordx4 v142, s[20:21]
	s_add_i32 m0, s24, 0x14000
	s_nop 0
	global_load_lds_dwordx4 v138, vcc
	s_add_i32 m0, s24, 0x16000
	s_nop 0
	global_load_lds_dwordx4 v142, vcc
	s_mov_b32 m0, s24
	s_nop 0
	global_load_lds_dwordx4 v136, s[22:23]
	s_add_i32 m0, s24, 0x2000
	s_nop 0
	global_load_lds_dwordx4 v140, s[22:23]
	s_waitcnt lgkmcnt(0)
	s_setprio 1
	v_mfma_f32_16x16x32_bf16 v[92:95], v[128:131], v[182:185], v[92:95]
	v_mfma_f32_16x16x32_bf16 v[92:95], v[132:135], v[186:189], v[92:95]
	v_mfma_f32_16x16x32_bf16 v[84:87], v[128:131], v[190:193], v[84:87]
	v_mfma_f32_16x16x32_bf16 v[84:87], v[132:135], v[194:197], v[84:87]
	v_mfma_f32_16x16x32_bf16 v[76:79], v[128:131], v[198:201], v[76:79]
	v_mfma_f32_16x16x32_bf16 v[76:79], v[132:135], v[202:205], v[76:79]
	v_mfma_f32_16x16x32_bf16 v[60:63], v[128:131], v[206:209], v[60:63]
	v_mfma_f32_16x16x32_bf16 v[60:63], v[132:135], v[210:213], v[60:63]
	v_mfma_f32_16x16x32_bf16 v[56:59], v[150:153], v[206:209], v[56:59]
	v_mfma_f32_16x16x32_bf16 v[56:59], v[162:165], v[210:213], v[56:59]
	v_mfma_f32_16x16x32_bf16 v[72:75], v[150:153], v[198:201], v[72:75]
	v_mfma_f32_16x16x32_bf16 v[72:75], v[162:165], v[202:205], v[72:75]
	v_mfma_f32_16x16x32_bf16 v[80:83], v[150:153], v[190:193], v[80:83]
	v_mfma_f32_16x16x32_bf16 v[80:83], v[162:165], v[194:197], v[80:83]
	v_mfma_f32_16x16x32_bf16 v[88:91], v[150:153], v[182:185], v[88:91]
	v_mfma_f32_16x16x32_bf16 v[88:91], v[162:165], v[186:189], v[88:91]
	v_mfma_f32_16x16x32_bf16 v[28:31], v[166:169], v[182:185], v[28:31]
	v_mfma_f32_16x16x32_bf16 v[28:31], v[170:173], v[186:189], v[28:31]
	v_mfma_f32_16x16x32_bf16 v[20:23], v[166:169], v[190:193], v[20:23]
	v_mfma_f32_16x16x32_bf16 v[20:23], v[170:173], v[194:197], v[20:23]
	v_mfma_f32_16x16x32_bf16 v[12:15], v[166:169], v[198:201], v[12:15]
	v_mfma_f32_16x16x32_bf16 v[12:15], v[170:173], v[202:205], v[12:15]
	v_mfma_f32_16x16x32_bf16 v[4:7], v[166:169], v[206:209], v[4:7]
	v_mfma_f32_16x16x32_bf16 v[4:7], v[170:173], v[210:213], v[4:7]
	v_mfma_f32_16x16x32_bf16 v[0:3], v[174:177], v[206:209], v[0:3]
	v_mfma_f32_16x16x32_bf16 v[0:3], v[178:181], v[210:213], v[0:3]
	v_mfma_f32_16x16x32_bf16 v[8:11], v[174:177], v[198:201], v[8:11]
	v_mfma_f32_16x16x32_bf16 v[8:11], v[178:181], v[202:205], v[8:11]
	v_mfma_f32_16x16x32_bf16 v[16:19], v[174:177], v[190:193], v[16:19]
	v_mfma_f32_16x16x32_bf16 v[16:19], v[178:181], v[194:197], v[16:19]
	v_mfma_f32_16x16x32_bf16 v[24:27], v[174:177], v[182:185], v[24:27]
	v_mfma_f32_16x16x32_bf16 v[24:27], v[178:181], v[186:189], v[24:27]
	s_setprio 0
	s_waitcnt vmcnt(8)
	s_barrier
; #define PG8_STAGE(bufoff, gbase, voff) do { _Pragma("unroll") for (int _i = 0; _i < 2; ++_i) \
;         __builtin_amdgcn_global_load_lds((const unsigned*)((const char*)(gbase) + (voff)[_i]), (PG8_LAS unsigned*)(lds + (bufoff) + ldsw + _i * 8192), 16, 0, 0); } while (0)
; #define PG8_LDA(dst, b, h) do { _Pragma("unroll") for (int m = 0; m < 4; ++m) _Pragma("unroll") for (int k = 0; k < 2; ++k) dst[m][k] = *(const PG8_LAS bf16x8*)(lds + PG8_SA(b, h) + aoff + m * 2048 + k * 1024); } while (0)
; #define PG8_LDB(dst, b, h) do { _Pragma("unroll") for (int n = 0; n < 2; ++n) _Pragma("unroll") for (int k = 0; k < 2; ++k) dst[n][k] = *(const PG8_LAS bf16x8*)(lds + PG8_SB(b, h) + boff + n * 2048 + k * 1024); } while (0)
; #define PG8_MMA(ai, bj, At, Bt) do { __builtin_amdgcn_s_setprio(1); _Pragma("unroll") for (int m = 0; m < 4; ++m) _Pragma("unroll") for (int n = 0; n < 2; ++n) _Pragma("unroll") for (int k = 0; k < 2; ++k) \
;         acc[ai][bj][m][n] = __builtin_amdgcn_mfma_f32_16x16x32_bf16(Bt[n][k], At[m][k], acc[ai][bj][m][n], 0, 0, 0); __builtin_amdgcn_s_setprio(0); } while (0)
; #define PG8_WAIT_V(n) asm volatile("s_waitcnt vmcnt(" #n ")" ::: "memory")
; #define PG8_WAIT_L(n) asm volatile("s_waitcnt lgkmcnt(" #n ")" ::: "memory")
; #define PG8_BAR __builtin_amdgcn_s_barrier()
; #define PG8_SCHED __builtin_amdgcn_sched_barrier(0)
; template <class Epi, class Sched, bool ALIGN_EPI = false, bool SP2 = false>
; __device__ __forceinline__ void gemm_phase(PG8_LAS unsigned char* lds, const Gemm g, const Sched& S, const Epi& E) {
;     ...
;         for (int t = 0; t < nt; t += 2) {
;     ...
;             PG8_LDB(B0, 1, 0); PG8_LDB(B1, 1, 1); PG8_SCHED; PG8_LDA(At, 1, 0); PG8_STAGE(PG8_SA(0, 1), a2 + hstep, voffA);
;             PG8_WAIT_V(8); PG8_WAIT_L(0); PG8_BAR; PG8_MMA(0, 0, At, B0); PG8_MMA(0, 1, At, B1); PG8_BAR; PG8_SCHED;
;             PG8_LDA(At, 1, 1); PG8_STAGE(PG8_SB(1, 0), b3, voffB); PG8_STAGE(PG8_SB(1, 1), b3 + hstep, voffB); PG8_STAGE(PG8_SA(1, 0), a3, voffA);
;             PG8_WAIT_V(8); PG8_WAIT_L(0); PG8_BAR; PG8_MMA(1, 0, At, B0); PG8_MMA(1, 1, At, B1); PG8_BAR; PG8_SCHED;
	ds_read_b128 v[128:131], v159
	ds_read_b128 v[132:135], v159 offset:1024
	ds_read_b128 v[150:153], v159 offset:2048
	ds_read_b128 v[162:165], v159 offset:3072
	ds_read_b128 v[166:169], v160
	ds_read_b128 v[170:173], v160 offset:1024
	ds_read_b128 v[174:177], v160 offset:2048
	ds_read_b128 v[178:181], v160 offset:3072
	ds_read_b128 v[182:185], v158 offset:32768
	ds_read_b128 v[186:189], v158 offset:33792
	ds_read_b128 v[190:193], v158 offset:34816
	ds_read_b128 v[194:197], v158 offset:35840
	ds_read_b128 v[198:201], v158 offset:36864
	ds_read_b128 v[202:205], v158 offset:37888
	ds_read_b128 v[206:209], v158 offset:38912
	ds_read_b128 v[210:213], v158 offset:39936
	s_add_u32 vcc_lo, s22, 0x404000
	s_addc_u32 vcc_hi, s23, 0
	s_add_i32 m0, s24, 0x4000
	s_nop 0
	global_load_lds_dwordx4 v136, vcc
	s_add_i32 m0, s24, 0x6000
	s_nop 0
	global_load_lds_dwordx4 v140, vcc
	s_waitcnt lgkmcnt(0)
	s_setprio 1
	v_mfma_f32_16x16x32_bf16 v[124:127], v[128:131], v[182:185], v[124:127]
	v_mfma_f32_16x16x32_bf16 v[124:127], v[132:135], v[186:189], v[124:127]
	v_mfma_f32_16x16x32_bf16 v[116:119], v[128:131], v[190:193], v[116:119]
	v_mfma_f32_16x16x32_bf16 v[116:119], v[132:135], v[194:197], v[116:119]
	v_mfma_f32_16x16x32_bf16 v[108:111], v[128:131], v[198:201], v[108:111]
	v_mfma_f32_16x16x32_bf16 v[108:111], v[132:135], v[202:205], v[108:111]
	v_mfma_f32_16x16x32_bf16 v[100:103], v[128:131], v[206:209], v[100:103]
	v_mfma_f32_16x16x32_bf16 v[100:103], v[132:135], v[210:213], v[100:103]
	v_mfma_f32_16x16x32_bf16 v[96:99], v[150:153], v[206:209], v[96:99]
	v_mfma_f32_16x16x32_bf16 v[96:99], v[162:165], v[210:213], v[96:99]
	v_mfma_f32_16x16x32_bf16 v[104:107], v[150:153], v[198:201], v[104:107]
	v_mfma_f32_16x16x32_bf16 v[104:107], v[162:165], v[202:205], v[104:107]
	v_mfma_f32_16x16x32_bf16 v[112:115], v[150:153], v[190:193], v[112:115]
	v_mfma_f32_16x16x32_bf16 v[112:115], v[162:165], v[194:197], v[112:115]
	v_mfma_f32_16x16x32_bf16 v[120:123], v[150:153], v[182:185], v[120:123]
	v_mfma_f32_16x16x32_bf16 v[120:123], v[162:165], v[186:189], v[120:123]
	v_mfma_f32_16x16x32_bf16 v[68:71], v[166:169], v[182:185], v[68:71]
	v_mfma_f32_16x16x32_bf16 v[68:71], v[170:173], v[186:189], v[68:71]
	v_mfma_f32_16x16x32_bf16 v[52:55], v[166:169], v[190:193], v[52:55]
	v_mfma_f32_16x16x32_bf16 v[52:55], v[170:173], v[194:197], v[52:55]
	v_mfma_f32_16x16x32_bf16 v[44:47], v[166:169], v[198:201], v[44:47]
	v_mfma_f32_16x16x32_bf16 v[44:47], v[170:173], v[202:205], v[44:47]
	v_mfma_f32_16x16x32_bf16 v[36:39], v[166:169], v[206:209], v[36:39]
	v_mfma_f32_16x16x32_bf16 v[36:39], v[170:173], v[210:213], v[36:39]
	v_mfma_f32_16x16x32_bf16 v[32:35], v[174:177], v[206:209], v[32:35]
	v_mfma_f32_16x16x32_bf16 v[32:35], v[178:181], v[210:213], v[32:35]
	v_mfma_f32_16x16x32_bf16 v[40:43], v[174:177], v[198:201], v[40:43]
	v_mfma_f32_16x16x32_bf16 v[40:43], v[178:181], v[202:205], v[40:43]
	v_mfma_f32_16x16x32_bf16 v[48:51], v[174:177], v[190:193], v[48:51]
	v_mfma_f32_16x16x32_bf16 v[48:51], v[178:181], v[194:197], v[48:51]
	v_mfma_f32_16x16x32_bf16 v[64:67], v[174:177], v[182:185], v[64:67]
	v_mfma_f32_16x16x32_bf16 v[64:67], v[178:181], v[186:189], v[64:67]
	s_setprio 0
	s_waitcnt vmcnt(8)
	s_barrier
	ds_read_b128 v[182:185], v158 offset:49152
	ds_read_b128 v[186:189], v158 offset:50176
	ds_read_b128 v[190:193], v158 offset:51200
	ds_read_b128 v[194:197], v158 offset:52224
	ds_read_b128 v[198:201], v158 offset:53248
	ds_read_b128 v[202:205], v158 offset:54272
	ds_read_b128 v[206:209], v158 offset:55296
	ds_read_b128 v[210:213], v158 offset:56320
	s_add_u32 s60, s20, 0x80
	s_addc_u32 s61, s21, 0
	s_add_u32 vcc_lo, s60, 0x404000
	s_addc_u32 vcc_hi, s61, 0
	s_add_i32 m0, s24, 0x18000
	s_nop 0
	global_load_lds_dwordx4 v138, s[60:61]
	s_add_i32 m0, s24, 0x1a000
	s_nop 0
	global_load_lds_dwordx4 v142, s[60:61]
	s_add_i32 m0, s24, 0x1c000
	s_nop 0
	global_load_lds_dwordx4 v138, vcc
	s_add_i32 m0, s24, 0x1e000
	s_nop 0
	global_load_lds_dwordx4 v142, vcc
	s_add_u32 s60, s22, 0x80
	s_addc_u32 s61, s23, 0
	s_add_i32 m0, s24, 0x8000
	s_nop 0
	global_load_lds_dwordx4 v136, s[60:61]
	s_add_i32 m0, s24, 0xa000
	s_nop 0
	global_load_lds_dwordx4 v140, s[60:61]
	s_waitcnt lgkmcnt(0)
	s_setprio 1
	v_mfma_f32_16x16x32_bf16 v[92:95], v[128:131], v[182:185], v[92:95]
	v_mfma_f32_16x16x32_bf16 v[92:95], v[132:135], v[186:189], v[92:95]
	v_mfma_f32_16x16x32_bf16 v[84:87], v[128:131], v[190:193], v[84:87]
	v_mfma_f32_16x16x32_bf16 v[84:87], v[132:135], v[194:197], v[84:87]
	v_mfma_f32_16x16x32_bf16 v[76:79], v[128:131], v[198:201], v[76:79]
	v_mfma_f32_16x16x32_bf16 v[76:79], v[132:135], v[202:205], v[76:79]
	v_mfma_f32_16x16x32_bf16 v[60:63], v[128:131], v[206:209], v[60:63]
	v_mfma_f32_16x16x32_bf16 v[60:63], v[132:135], v[210:213], v[60:63]
	v_mfma_f32_16x16x32_bf16 v[56:59], v[150:153], v[206:209], v[56:59]
	v_mfma_f32_16x16x32_bf16 v[56:59], v[162:165], v[210:213], v[56:59]
	v_mfma_f32_16x16x32_bf16 v[72:75], v[150:153], v[198:201], v[72:75]
	v_mfma_f32_16x16x32_bf16 v[72:75], v[162:165], v[202:205], v[72:75]
	v_mfma_f32_16x16x32_bf16 v[80:83], v[150:153], v[190:193], v[80:83]
	v_mfma_f32_16x16x32_bf16 v[80:83], v[162:165], v[194:197], v[80:83]
	v_mfma_f32_16x16x32_bf16 v[88:91], v[150:153], v[182:185], v[88:91]
	v_mfma_f32_16x16x32_bf16 v[88:91], v[162:165], v[186:189], v[88:91]
	v_mfma_f32_16x16x32_bf16 v[28:31], v[166:169], v[182:185], v[28:31]
	v_mfma_f32_16x16x32_bf16 v[28:31], v[170:173], v[186:189], v[28:31]
	v_mfma_f32_16x16x32_bf16 v[20:23], v[166:169], v[190:193], v[20:23]
	v_mfma_f32_16x16x32_bf16 v[20:23], v[170:173], v[194:197], v[20:23]
	v_mfma_f32_16x16x32_bf16 v[12:15], v[166:169], v[198:201], v[12:15]
	v_mfma_f32_16x16x32_bf16 v[12:15], v[170:173], v[202:205], v[12:15]
	v_mfma_f32_16x16x32_bf16 v[4:7], v[166:169], v[206:209], v[4:7]
	v_mfma_f32_16x16x32_bf16 v[4:7], v[170:173], v[210:213], v[4:7]
	v_mfma_f32_16x16x32_bf16 v[0:3], v[174:177], v[206:209], v[0:3]
	v_mfma_f32_16x16x32_bf16 v[0:3], v[178:181], v[210:213], v[0:3]
	v_mfma_f32_16x16x32_bf16 v[8:11], v[174:177], v[198:201], v[8:11]
	v_mfma_f32_16x16x32_bf16 v[8:11], v[178:181], v[202:205], v[8:11]
	v_mfma_f32_16x16x32_bf16 v[16:19], v[174:177], v[190:193], v[16:19]
	v_mfma_f32_16x16x32_bf16 v[16:19], v[178:181], v[194:197], v[16:19]
	v_mfma_f32_16x16x32_bf16 v[24:27], v[174:177], v[182:185], v[24:27]
	v_mfma_f32_16x16x32_bf16 v[24:27], v[178:181], v[186:189], v[24:27]
	s_setprio 0
	s_waitcnt vmcnt(8)
	s_barrier
	s_add_i32 s59, s59, 2
	s_add_u32 s18, s18, 0x100
	s_addc_u32 s19, s19, 0
	s_add_u32 s57, s57, 0x100
	s_addc_u32 s58, s58, 0
	s_cmpk_gt_u32 s59, 0xfd
	s_cbranch_scc0 .LBB0_1321
	s_branch .Lf2_exit
; #define PG8_STAGE(bufoff, gbase, voff) do { _Pragma("unroll") for (int _i = 0; _i < 2; ++_i) \
;         __builtin_amdgcn_global_load_lds((const unsigned*)((const char*)(gbase) + (voff)[_i]), (PG8_LAS unsigned*)(lds + (bufoff) + ldsw + _i * 8192), 16, 0, 0); } while (0)
; #define PG8_LDA(dst, b, h) do { _Pragma("unroll") for (int m = 0; m < 4; ++m) _Pragma("unroll") for (int k = 0; k < 2; ++k) dst[m][k] = *(const PG8_LAS bf16x8*)(lds + PG8_SA(b, h) + aoff + m * 2048 + k * 1024); } while (0)
; #define PG8_LDB(dst, b, h) do { _Pragma("unroll") for (int n = 0; n < 2; ++n) _Pragma("unroll") for (int k = 0; k < 2; ++k) dst[n][k] = *(const PG8_LAS bf16x8*)(lds + PG8_SB(b, h) + boff + n * 2048 + k * 1024); } while (0)
; #define PG8_MMA(ai, bj, At, Bt) do { __builtin_amdgcn_s_setprio(1); _Pragma("unroll") for (int m = 0; m < 4; ++m) _Pragma("unroll") for (int n = 0; n < 2; ++n) _Pragma("unroll") for (int k = 0; k < 2; ++k) \
;         acc[ai][bj][m][n] = __builtin_amdgcn_mfma_f32_16x16x32_bf16(Bt[n][k], At[m][k], acc[ai][bj][m][n], 0, 0, 0); __builtin_amdgcn_s_setprio(0); } while (0)
; #define PG8_WAIT_V(n) asm volatile("s_waitcnt vmcnt(" #n ")" ::: "memory")
; #define PG8_WAIT_L(n) asm volatile("s_waitcnt lgkmcnt(" #n ")" ::: "memory")
; #define PG8_BAR __builtin_amdgcn_s_barrier()
; #define PG8_SCHED __builtin_amdgcn_sched_barrier(0)
; template <class Epi, class Sched, bool ALIGN_EPI = false, bool SP2 = false>
; __device__ __forceinline__ void gemm_phase(PG8_LAS unsigned char* lds, const Gemm g, const Sched& S, const Epi& E) {
;     ...
;             const bool last = (t == nt - 2);
;             const char* a1 = cA + (size_t)(t + 1) * kstep;
;             const char* a2 = last ? nA : cA + (size_t)(t + 2) * kstep; const char* b2 = last ? nB : cB + (size_t)(t + 2) * kstep;
;             const char* a3 = a2 + kstep; const char* b3 = b2 + kstep;
;     ...
;             PG8_LDB(B0, 0, 0); PG8_LDB(B1, 0, 1); PG8_SCHED; PG8_LDA(At, 0, 0); PG8_STAGE(PG8_SA(1, 1), a1 + hstep, voffA);
;             PG8_WAIT_V(8); PG8_WAIT_L(0); PG8_BAR; PG8_MMA(0, 0, At, B0); PG8_MMA(0, 1, At, B1); PG8_BAR; PG8_SCHED;
;             PG8_LDA(At, 0, 1); PG8_STAGE(PG8_SB(0, 0), b2, voffB); PG8_STAGE(PG8_SB(0, 1), b2 + hstep, voffB); PG8_STAGE(PG8_SA(0, 0), a2, voffA);
;             PG8_WAIT_V(8); PG8_WAIT_L(0); PG8_BAR; PG8_MMA(1, 0, At, B0); PG8_MMA(1, 1, At, B1); PG8_BAR; PG8_SCHED;
.Lf2_h1:
	ds_read_b128 v[128:131], v156
	ds_read_b128 v[132:135], v156 offset:1024
	ds_read_b128 v[150:153], v156 offset:2048
	ds_read_b128 v[162:165], v156 offset:3072
	ds_read_b128 v[166:169], v157
	ds_read_b128 v[170:173], v157 offset:1024
	ds_read_b128 v[174:177], v157 offset:2048
	ds_read_b128 v[178:181], v157 offset:3072
	s_add_u32 s20, s18, 0xffbfc080
	s_addc_u32 s21, s19, -1
	s_cmpk_eq_i32 s59, 0xfc
	s_cselect_b32 s23, s7, s21
	s_cselect_b32 s22, s6, s20
	s_cselect_b32 s21, s17, s58
	s_cselect_b32 s20, s16, s57
	ds_read_b128 v[182:185], v158
	ds_read_b128 v[186:189], v158 offset:1024
	ds_read_b128 v[190:193], v158 offset:2048
	ds_read_b128 v[194:197], v158 offset:3072
	ds_read_b128 v[198:201], v158 offset:4096
	ds_read_b128 v[202:205], v158 offset:5120
	ds_read_b128 v[206:209], v158 offset:6144
	ds_read_b128 v[210:213], v158 offset:7168
	s_add_i32 m0, s24, 0xc000
	s_nop 0
	global_load_lds_dwordx4 v136, s[18:19]
	s_add_i32 m0, s24, 0xe000
	s_nop 0
	global_load_lds_dwordx4 v140, s[18:19]
	s_sleep 2
	s_waitcnt lgkmcnt(0)
	s_waitcnt vmcnt(8)
	s_barrier
	s_setprio 2
	v_mfma_f32_16x16x32_bf16 v[124:127], v[128:131], v[182:185], v[124:127]
	v_mfma_f32_16x16x32_bf16 v[124:127], v[132:135], v[186:189], v[124:127]
	v_mfma_f32_16x16x32_bf16 v[116:119], v[128:131], v[190:193], v[116:119]
	v_mfma_f32_16x16x32_bf16 v[116:119], v[132:135], v[194:197], v[116:119]
	v_mfma_f32_16x16x32_bf16 v[108:111], v[128:131], v[198:201], v[108:111]
	v_mfma_f32_16x16x32_bf16 v[108:111], v[132:135], v[202:205], v[108:111]
	v_mfma_f32_16x16x32_bf16 v[100:103], v[128:131], v[206:209], v[100:103]
	v_mfma_f32_16x16x32_bf16 v[100:103], v[132:135], v[210:213], v[100:103]
	v_mfma_f32_16x16x32_bf16 v[96:99], v[150:153], v[206:209], v[96:99]
	v_mfma_f32_16x16x32_bf16 v[96:99], v[162:165], v[210:213], v[96:99]
	v_mfma_f32_16x16x32_bf16 v[104:107], v[150:153], v[198:201], v[104:107]
	v_mfma_f32_16x16x32_bf16 v[104:107], v[162:165], v[202:205], v[104:107]
	v_mfma_f32_16x16x32_bf16 v[112:115], v[150:153], v[190:193], v[112:115]
	v_mfma_f32_16x16x32_bf16 v[112:115], v[162:165], v[194:197], v[112:115]
	v_mfma_f32_16x16x32_bf16 v[120:123], v[150:153], v[182:185], v[120:123]
	v_mfma_f32_16x16x32_bf16 v[120:123], v[162:165], v[186:189], v[120:123]
	v_mfma_f32_16x16x32_bf16 v[68:71], v[166:169], v[182:185], v[68:71]
	v_mfma_f32_16x16x32_bf16 v[68:71], v[170:173], v[186:189], v[68:71]
	v_mfma_f32_16x16x32_bf16 v[52:55], v[166:169], v[190:193], v[52:55]
	v_mfma_f32_16x16x32_bf16 v[52:55], v[170:173], v[194:197], v[52:55]
	v_mfma_f32_16x16x32_bf16 v[44:47], v[166:169], v[198:201], v[44:47]
	v_mfma_f32_16x16x32_bf16 v[44:47], v[170:173], v[202:205], v[44:47]
	v_mfma_f32_16x16x32_bf16 v[36:39], v[166:169], v[206:209], v[36:39]
	v_mfma_f32_16x16x32_bf16 v[36:39], v[170:173], v[210:213], v[36:39]
	v_mfma_f32_16x16x32_bf16 v[32:35], v[174:177], v[206:209], v[32:35]
	v_mfma_f32_16x16x32_bf16 v[32:35], v[178:181], v[210:213], v[32:35]
	v_mfma_f32_16x16x32_bf16 v[40:43], v[174:177], v[198:201], v[40:43]
	v_mfma_f32_16x16x32_bf16 v[40:43], v[178:181], v[202:205], v[40:43]
	v_mfma_f32_16x16x32_bf16 v[48:51], v[174:177], v[190:193], v[48:51]
	v_mfma_f32_16x16x32_bf16 v[48:51], v[178:181], v[194:197], v[48:51]
	v_mfma_f32_16x16x32_bf16 v[64:67], v[174:177], v[182:185], v[64:67]
	v_mfma_f32_16x16x32_bf16 v[64:67], v[178:181], v[186:189], v[64:67]
	s_setprio 0
	ds_read_b128 v[182:185], v158 offset:16384
	ds_read_b128 v[186:189], v158 offset:17408
	ds_read_b128 v[190:193], v158 offset:18432
	ds_read_b128 v[194:197], v158 offset:19456
	ds_read_b128 v[198:201], v158 offset:20480
	ds_read_b128 v[202:205], v158 offset:21504
	ds_read_b128 v[206:209], v158 offset:22528
	ds_read_b128 v[210:213], v158 offset:23552
	s_add_u32 vcc_lo, s20, 0x404000
	s_addc_u32 vcc_hi, s21, 0
	s_add_i32 m0, s24, 0x10000
	s_nop 0
	global_load_lds_dwordx4 v138, s[20:21]
	s_add_i32 m0, s24, 0x12000
	s_nop 0
	global_load_lds_dwordx4 v142, s[20:21]
	s_add_i32 m0, s24, 0x14000
	s_nop 0
	global_load_lds_dwordx4 v138, vcc
	s_add_i32 m0, s24, 0x16000
	s_nop 0
	global_load_lds_dwordx4 v142, vcc
	s_mov_b32 m0, s24
	s_nop 0
	global_load_lds_dwordx4 v136, s[22:23]
	s_add_i32 m0, s24, 0x2000
	s_nop 0
	global_load_lds_dwordx4 v140, s[22:23]
	s_sleep 2
	s_waitcnt lgkmcnt(0)
	s_waitcnt vmcnt(8)
	s_barrier
; #define PG8_STAGE(bufoff, gbase, voff) do { _Pragma("unroll") for (int _i = 0; _i < 2; ++_i) \
;         __builtin_amdgcn_global_load_lds((const unsigned*)((const char*)(gbase) + (voff)[_i]), (PG8_LAS unsigned*)(lds + (bufoff) + ldsw + _i * 8192), 16, 0, 0); } while (0)
; #define PG8_LDA(dst, b, h) do { _Pragma("unroll") for (int m = 0; m < 4; ++m) _Pragma("unroll") for (int k = 0; k < 2; ++k) dst[m][k] = *(const PG8_LAS bf16x8*)(lds + PG8_SA(b, h) + aoff + m * 2048 + k * 1024); } while (0)
; #define PG8_LDB(dst, b, h) do { _Pragma("unroll") for (int n = 0; n < 2; ++n) _Pragma("unroll") for (int k = 0; k < 2; ++k) dst[n][k] = *(const PG8_LAS bf16x8*)(lds + PG8_SB(b, h) + boff + n * 2048 + k * 1024); } while (0)
; #define PG8_MMA(ai, bj, At, Bt) do { __builtin_amdgcn_s_setprio(1); _Pragma("unroll") for (int m = 0; m < 4; ++m) _Pragma("unroll") for (int n = 0; n < 2; ++n) _Pragma("unroll") for (int k = 0; k < 2; ++k) \
;         acc[ai][bj][m][n] = __builtin_amdgcn_mfma_f32_16x16x32_bf16(Bt[n][k], At[m][k], acc[ai][bj][m][n], 0, 0, 0); __builtin_amdgcn_s_setprio(0); } while (0)
; #define PG8_WAIT_V(n) asm volatile("s_waitcnt vmcnt(" #n ")" ::: "memory")
; #define PG8_WAIT_L(n) asm volatile("s_waitcnt lgkmcnt(" #n ")" ::: "memory")
; #define PG8_BAR __builtin_amdgcn_s_barrier()
; #define PG8_SCHED __builtin_amdgcn_sched_barrier(0)
; template <class Epi, class Sched, bool ALIGN_EPI = false, bool SP2 = false>
; __device__ __forceinline__ void gemm_phase(PG8_LAS unsigned char* lds, const Gemm g, const Sched& S, const Epi& E) {
;     ...
;             PG8_WAIT_V(8); PG8_WAIT_L(0); PG8_BAR; PG8_MMA(1, 0, At, B0); PG8_MMA(1, 1, At, B1); PG8_BAR; PG8_SCHED;
;             PG8_LDB(B0, 1, 0); PG8_LDB(B1, 1, 1); PG8_SCHED; PG8_LDA(At, 1, 0); PG8_STAGE(PG8_SA(0, 1), a2 + hstep, voffA);
;             PG8_WAIT_V(8); PG8_WAIT_L(0); PG8_BAR; PG8_MMA(0, 0, At, B0); PG8_MMA(0, 1, At, B1); PG8_BAR; PG8_SCHED;
	s_setprio 2
	v_mfma_f32_16x16x32_bf16 v[92:95], v[128:131], v[182:185], v[92:95]
	v_mfma_f32_16x16x32_bf16 v[92:95], v[132:135], v[186:189], v[92:95]
	v_mfma_f32_16x16x32_bf16 v[84:87], v[128:131], v[190:193], v[84:87]
	v_mfma_f32_16x16x32_bf16 v[84:87], v[132:135], v[194:197], v[84:87]
	v_mfma_f32_16x16x32_bf16 v[76:79], v[128:131], v[198:201], v[76:79]
	v_mfma_f32_16x16x32_bf16 v[76:79], v[132:135], v[202:205], v[76:79]
	v_mfma_f32_16x16x32_bf16 v[60:63], v[128:131], v[206:209], v[60:63]
	v_mfma_f32_16x16x32_bf16 v[60:63], v[132:135], v[210:213], v[60:63]
	v_mfma_f32_16x16x32_bf16 v[56:59], v[150:153], v[206:209], v[56:59]
	v_mfma_f32_16x16x32_bf16 v[56:59], v[162:165], v[210:213], v[56:59]
	v_mfma_f32_16x16x32_bf16 v[72:75], v[150:153], v[198:201], v[72:75]
	v_mfma_f32_16x16x32_bf16 v[72:75], v[162:165], v[202:205], v[72:75]
	v_mfma_f32_16x16x32_bf16 v[80:83], v[150:153], v[190:193], v[80:83]
	v_mfma_f32_16x16x32_bf16 v[80:83], v[162:165], v[194:197], v[80:83]
	v_mfma_f32_16x16x32_bf16 v[88:91], v[150:153], v[182:185], v[88:91]
	v_mfma_f32_16x16x32_bf16 v[88:91], v[162:165], v[186:189], v[88:91]
	v_mfma_f32_16x16x32_bf16 v[28:31], v[166:169], v[182:185], v[28:31]
	v_mfma_f32_16x16x32_bf16 v[28:31], v[170:173], v[186:189], v[28:31]
	v_mfma_f32_16x16x32_bf16 v[20:23], v[166:169], v[190:193], v[20:23]
	v_mfma_f32_16x16x32_bf16 v[20:23], v[170:173], v[194:197], v[20:23]
	v_mfma_f32_16x16x32_bf16 v[12:15], v[166:169], v[198:201], v[12:15]
	v_mfma_f32_16x16x32_bf16 v[12:15], v[170:173], v[202:205], v[12:15]
	v_mfma_f32_16x16x32_bf16 v[4:7], v[166:169], v[206:209], v[4:7]
	v_mfma_f32_16x16x32_bf16 v[4:7], v[170:173], v[210:213], v[4:7]
	v_mfma_f32_16x16x32_bf16 v[0:3], v[174:177], v[206:209], v[0:3]
	v_mfma_f32_16x16x32_bf16 v[0:3], v[178:181], v[210:213], v[0:3]
	v_mfma_f32_16x16x32_bf16 v[8:11], v[174:177], v[198:201], v[8:11]
	v_mfma_f32_16x16x32_bf16 v[8:11], v[178:181], v[202:205], v[8:11]
	v_mfma_f32_16x16x32_bf16 v[16:19], v[174:177], v[190:193], v[16:19]
	v_mfma_f32_16x16x32_bf16 v[16:19], v[178:181], v[194:197], v[16:19]
	v_mfma_f32_16x16x32_bf16 v[24:27], v[174:177], v[182:185], v[24:27]
	v_mfma_f32_16x16x32_bf16 v[24:27], v[178:181], v[186:189], v[24:27]
	s_setprio 0
	ds_read_b128 v[128:131], v159
	ds_read_b128 v[132:135], v159 offset:1024
	ds_read_b128 v[150:153], v159 offset:2048
	ds_read_b128 v[162:165], v159 offset:3072
	ds_read_b128 v[166:169], v160
	ds_read_b128 v[170:173], v160 offset:1024
	ds_read_b128 v[174:177], v160 offset:2048
	ds_read_b128 v[178:181], v160 offset:3072
	ds_read_b128 v[182:185], v158 offset:32768
	ds_read_b128 v[186:189], v158 offset:33792
	ds_read_b128 v[190:193], v158 offset:34816
	ds_read_b128 v[194:197], v158 offset:35840
	ds_read_b128 v[198:201], v158 offset:36864
	ds_read_b128 v[202:205], v158 offset:37888
	ds_read_b128 v[206:209], v158 offset:38912
	ds_read_b128 v[210:213], v158 offset:39936
	s_add_u32 vcc_lo, s22, 0x404000
	s_addc_u32 vcc_hi, s23, 0
	s_add_i32 m0, s24, 0x4000
	s_nop 0
	global_load_lds_dwordx4 v136, vcc
	s_add_i32 m0, s24, 0x6000
	s_nop 0
	global_load_lds_dwordx4 v140, vcc
	s_sleep 2
	s_waitcnt lgkmcnt(0)
	s_waitcnt vmcnt(8)
	s_barrier
; #define PG8_STAGE(bufoff, gbase, voff) do { _Pragma("unroll") for (int _i = 0; _i < 2; ++_i) \
;         __builtin_amdgcn_global_load_lds((const unsigned*)((const char*)(gbase) + (voff)[_i]), (PG8_LAS unsigned*)(lds + (bufoff) + ldsw + _i * 8192), 16, 0, 0); } while (0)
; #define PG8_LDA(dst, b, h) do { _Pragma("unroll") for (int m = 0; m < 4; ++m) _Pragma("unroll") for (int k = 0; k < 2; ++k) dst[m][k] = *(const PG8_LAS bf16x8*)(lds + PG8_SA(b, h) + aoff + m * 2048 + k * 1024); } while (0)
; #define PG8_MMA(ai, bj, At, Bt) do { __builtin_amdgcn_s_setprio(1); _Pragma("unroll") for (int m = 0; m < 4; ++m) _Pragma("unroll") for (int n = 0; n < 2; ++n) _Pragma("unroll") for (int k = 0; k < 2; ++k) \
;         acc[ai][bj][m][n] = __builtin_amdgcn_mfma_f32_16x16x32_bf16(Bt[n][k], At[m][k], acc[ai][bj][m][n], 0, 0, 0); __builtin_amdgcn_s_setprio(0); } while (0)
; #define PG8_WAIT_V(n) asm volatile("s_waitcnt vmcnt(" #n ")" ::: "memory")
; #define PG8_WAIT_L(n) asm volatile("s_waitcnt lgkmcnt(" #n ")" ::: "memory")
; #define PG8_BAR __builtin_amdgcn_s_barrier()
; #define PG8_SCHED __builtin_amdgcn_sched_barrier(0)
; template <class Epi, class Sched, bool ALIGN_EPI = false, bool SP2 = false>
; __device__ __forceinline__ void gemm_phase(PG8_LAS unsigned char* lds, const Gemm g, const Sched& S, const Epi& E) {
;     ...
;         for (int t = 0; t < nt; t += 2) {
;     ...
;             PG8_WAIT_V(8); PG8_WAIT_L(0); PG8_BAR; PG8_MMA(0, 0, At, B0); PG8_MMA(0, 1, At, B1); PG8_BAR; PG8_SCHED;
;             PG8_LDA(At, 1, 1); PG8_STAGE(PG8_SB(1, 0), b3, voffB); PG8_STAGE(PG8_SB(1, 1), b3 + hstep, voffB); PG8_STAGE(PG8_SA(1, 0), a3, voffA);
;             PG8_WAIT_V(8); PG8_WAIT_L(0); PG8_BAR; PG8_MMA(1, 0, At, B0); PG8_MMA(1, 1, At, B1); PG8_BAR; PG8_SCHED;
	s_setprio 2
	v_mfma_f32_16x16x32_bf16 v[124:127], v[128:131], v[182:185], v[124:127]
	v_mfma_f32_16x16x32_bf16 v[124:127], v[132:135], v[186:189], v[124:127]
	v_mfma_f32_16x16x32_bf16 v[116:119], v[128:131], v[190:193], v[116:119]
	v_mfma_f32_16x16x32_bf16 v[116:119], v[132:135], v[194:197], v[116:119]
	v_mfma_f32_16x16x32_bf16 v[108:111], v[128:131], v[198:201], v[108:111]
	v_mfma_f32_16x16x32_bf16 v[108:111], v[132:135], v[202:205], v[108:111]
	v_mfma_f32_16x16x32_bf16 v[100:103], v[128:131], v[206:209], v[100:103]
	v_mfma_f32_16x16x32_bf16 v[100:103], v[132:135], v[210:213], v[100:103]
	v_mfma_f32_16x16x32_bf16 v[96:99], v[150:153], v[206:209], v[96:99]
	v_mfma_f32_16x16x32_bf16 v[96:99], v[162:165], v[210:213], v[96:99]
	v_mfma_f32_16x16x32_bf16 v[104:107], v[150:153], v[198:201], v[104:107]
	v_mfma_f32_16x16x32_bf16 v[104:107], v[162:165], v[202:205], v[104:107]
	v_mfma_f32_16x16x32_bf16 v[112:115], v[150:153], v[190:193], v[112:115]
	v_mfma_f32_16x16x32_bf16 v[112:115], v[162:165], v[194:197], v[112:115]
	v_mfma_f32_16x16x32_bf16 v[120:123], v[150:153], v[182:185], v[120:123]
	v_mfma_f32_16x16x32_bf16 v[120:123], v[162:165], v[186:189], v[120:123]
	v_mfma_f32_16x16x32_bf16 v[68:71], v[166:169], v[182:185], v[68:71]
	v_mfma_f32_16x16x32_bf16 v[68:71], v[170:173], v[186:189], v[68:71]
	v_mfma_f32_16x16x32_bf16 v[52:55], v[166:169], v[190:193], v[52:55]
	v_mfma_f32_16x16x32_bf16 v[52:55], v[170:173], v[194:197], v[52:55]
	v_mfma_f32_16x16x32_bf16 v[44:47], v[166:169], v[198:201], v[44:47]
	v_mfma_f32_16x16x32_bf16 v[44:47], v[170:173], v[202:205], v[44:47]
	v_mfma_f32_16x16x32_bf16 v[36:39], v[166:169], v[206:209], v[36:39]
	v_mfma_f32_16x16x32_bf16 v[36:39], v[170:173], v[210:213], v[36:39]
	v_mfma_f32_16x16x32_bf16 v[32:35], v[174:177], v[206:209], v[32:35]
	v_mfma_f32_16x16x32_bf16 v[32:35], v[178:181], v[210:213], v[32:35]
	v_mfma_f32_16x16x32_bf16 v[40:43], v[174:177], v[198:201], v[40:43]
	v_mfma_f32_16x16x32_bf16 v[40:43], v[178:181], v[202:205], v[40:43]
	v_mfma_f32_16x16x32_bf16 v[48:51], v[174:177], v[190:193], v[48:51]
	v_mfma_f32_16x16x32_bf16 v[48:51], v[178:181], v[194:197], v[48:51]
	v_mfma_f32_16x16x32_bf16 v[64:67], v[174:177], v[182:185], v[64:67]
	v_mfma_f32_16x16x32_bf16 v[64:67], v[178:181], v[186:189], v[64:67]
	s_setprio 0
	ds_read_b128 v[182:185], v158 offset:49152
	ds_read_b128 v[186:189], v158 offset:50176
	ds_read_b128 v[190:193], v158 offset:51200
	ds_read_b128 v[194:197], v158 offset:52224
	ds_read_b128 v[198:201], v158 offset:53248
	ds_read_b128 v[202:205], v158 offset:54272
	ds_read_b128 v[206:209], v158 offset:55296
	ds_read_b128 v[210:213], v158 offset:56320
	s_add_u32 s60, s20, 0x80
	s_addc_u32 s61, s21, 0
	s_add_u32 vcc_lo, s60, 0x404000
	s_addc_u32 vcc_hi, s61, 0
	s_add_i32 m0, s24, 0x18000
	s_nop 0
	global_load_lds_dwordx4 v138, s[60:61]
	s_add_i32 m0, s24, 0x1a000
	s_nop 0
	global_load_lds_dwordx4 v142, s[60:61]
	s_add_i32 m0, s24, 0x1c000
	s_nop 0
	global_load_lds_dwordx4 v138, vcc
	s_add_i32 m0, s24, 0x1e000
	s_nop 0
	global_load_lds_dwordx4 v142, vcc
	s_add_u32 s60, s22, 0x80
	s_addc_u32 s61, s23, 0
	s_add_i32 m0, s24, 0x8000
	s_nop 0
	global_load_lds_dwordx4 v136, s[60:61]
	s_add_i32 m0, s24, 0xa000
	s_nop 0
	global_load_lds_dwordx4 v140, s[60:61]
	s_sleep 2
	s_waitcnt lgkmcnt(0)
	s_waitcnt vmcnt(8)
	s_barrier
	s_setprio 2
	v_mfma_f32_16x16x32_bf16 v[92:95], v[128:131], v[182:185], v[92:95]
	v_mfma_f32_16x16x32_bf16 v[92:95], v[132:135], v[186:189], v[92:95]
	v_mfma_f32_16x16x32_bf16 v[84:87], v[128:131], v[190:193], v[84:87]
	v_mfma_f32_16x16x32_bf16 v[84:87], v[132:135], v[194:197], v[84:87]
	v_mfma_f32_16x16x32_bf16 v[76:79], v[128:131], v[198:201], v[76:79]
	v_mfma_f32_16x16x32_bf16 v[76:79], v[132:135], v[202:205], v[76:79]
	v_mfma_f32_16x16x32_bf16 v[60:63], v[128:131], v[206:209], v[60:63]
	v_mfma_f32_16x16x32_bf16 v[60:63], v[132:135], v[210:213], v[60:63]
	v_mfma_f32_16x16x32_bf16 v[56:59], v[150:153], v[206:209], v[56:59]
	v_mfma_f32_16x16x32_bf16 v[56:59], v[162:165], v[210:213], v[56:59]
	v_mfma_f32_16x16x32_bf16 v[72:75], v[150:153], v[198:201], v[72:75]
	v_mfma_f32_16x16x32_bf16 v[72:75], v[162:165], v[202:205], v[72:75]
	v_mfma_f32_16x16x32_bf16 v[80:83], v[150:153], v[190:193], v[80:83]
	v_mfma_f32_16x16x32_bf16 v[80:83], v[162:165], v[194:197], v[80:83]
	v_mfma_f32_16x16x32_bf16 v[88:91], v[150:153], v[182:185], v[88:91]
	v_mfma_f32_16x16x32_bf16 v[88:91], v[162:165], v[186:189], v[88:91]
	v_mfma_f32_16x16x32_bf16 v[28:31], v[166:169], v[182:185], v[28:31]
	v_mfma_f32_16x16x32_bf16 v[28:31], v[170:173], v[186:189], v[28:31]
	v_mfma_f32_16x16x32_bf16 v[20:23], v[166:169], v[190:193], v[20:23]
	v_mfma_f32_16x16x32_bf16 v[20:23], v[170:173], v[194:197], v[20:23]
	v_mfma_f32_16x16x32_bf16 v[12:15], v[166:169], v[198:201], v[12:15]
	v_mfma_f32_16x16x32_bf16 v[12:15], v[170:173], v[202:205], v[12:15]
	v_mfma_f32_16x16x32_bf16 v[4:7], v[166:169], v[206:209], v[4:7]
	v_mfma_f32_16x16x32_bf16 v[4:7], v[170:173], v[210:213], v[4:7]
	v_mfma_f32_16x16x32_bf16 v[0:3], v[174:177], v[206:209], v[0:3]
	v_mfma_f32_16x16x32_bf16 v[0:3], v[178:181], v[210:213], v[0:3]
	v_mfma_f32_16x16x32_bf16 v[8:11], v[174:177], v[198:201], v[8:11]
	v_mfma_f32_16x16x32_bf16 v[8:11], v[178:181], v[202:205], v[8:11]
	v_mfma_f32_16x16x32_bf16 v[16:19], v[174:177], v[190:193], v[16:19]
	v_mfma_f32_16x16x32_bf16 v[16:19], v[178:181], v[194:197], v[16:19]
	v_mfma_f32_16x16x32_bf16 v[24:27], v[174:177], v[182:185], v[24:27]
	v_mfma_f32_16x16x32_bf16 v[24:27], v[178:181], v[186:189], v[24:27]
	s_setprio 0
	s_add_i32 s59, s59, 2
	s_add_u32 s18, s18, 0x100
	s_addc_u32 s19, s19, 0
	s_add_u32 s57, s57, 0x100
	s_addc_u32 s58, s58, 0
	s_cmpk_gt_u32 s59, 0xfd
	s_cbranch_scc0 .Lf2_h1
